# non-temporal (nt) hint on streamed-out result stores: in-proj and out-proj tile epilogues, LayerNorm f32 and bf16 row stores
# baseline (speedup 1.0000x reference)
; DI u16 f2bf(float x) { unsigned u = __float_as_uint(x); u += 0x7fffu + ((u >> 16) & 1u); return (u16)(u >> 16); }
; DI void phase_inproj(const Params& p, int layer, char* lds) {
;     ...
;     const int wr8 = w >> 2, wc8 = w & 3, fr = lane & 15, fq = lane >> 4;
; #pragma unroll
;     for (int bj = 0; bj < 2; ++bj)
; #pragma unroll
;       for (int n = 0; n < 2; ++n) {
;         const int cw = n0 + bj * 128 + wc8 * 32 + n * 16, col = cw + fr;
;         u16* dst = H + cw; int dstr = DIN;
;         {
;           const int bb = m0 / S;
;           if (cw >= C_DK && cw < C_DV) { const int o = cw - C_DK; dst = (u16*)(p.ws + OFF_DK) + ((size_t)(bb * 3 * S + (o >> 6) * S) << 6) + (o & 63); dstr = 64; }
;           else if (cw >= C_DV && cw < C_SQ) { const int o = cw - C_DV; dst = (u16*)(p.ws + OFF_DV) + ((size_t)(bb * 3 * S + (o >> 6) * S) << 6) + (o & 63); dstr = 64; }
;           else if (cw >= C_SK && cw < C_SV) { const int o = cw - C_SK; dst = (u16*)(p.ws + OFF_SK) + ((size_t)(bb * 1 * S + (o >> 6) * S) << 6) + (o & 63); dstr = 64; }
;           else if (cw >= C_SV && cw < C_GATE) { const int o = cw - C_SV; dst = (u16*)(p.ws + OFF_SV) + ((size_t)(bb * 1 * S + (o >> 6) * S) << 6) + (o & 63); dstr = 64; }
;         }
;         if (cw < DIN) {
;           float sc = 1.f;
;           if (col >= C_DQ && col < C_DK) sc = SC_DQ;
;           if (col >= C_SQ && col < C_SK) sc = SC_SQ;
;           const bool gate = col >= C_GATE;
; #pragma unroll
;           for (int ai = 0; ai < 2; ++ai)
; #pragma unroll
;             for (int m = 0; m < 4; ++m) {
; #pragma unroll
;               for (int j = 0; j < 4; ++j) {
;                 const int row = m0 + ai * 128 + wr8 * 64 + m * 16 + fq * 4 + j;
;                 float v = acc[ai][bj][m][n][j] * sc;
;                 if (gate) v = v * __builtin_amdgcn_rcpf(1.f + __expf(-v));
;                 dst[(size_t)row * dstr + fr] = f2bf(v);
;               }
;               __builtin_amdgcn_sched_barrier(0);
;             }
;         }
;       }
.Lipf_none:
	s_nop 7
	v_and_b32_e32 v140, 64, v144
	v_add_u32_e32 v140, v140, v130
	v_bfe_u32 v141, v144, 2, 2
	v_lshlrev_b32_e32 v141, 4, v141
	v_mov_b32_e32 v142, 0x15c0
	v_mul_u32_u24_e32 v132, v140, v142
	v_add_u32_e32 v132, v132, v141
	v_lshl_add_u32 v133, v140, 7, v141
	v_readfirstlane_b32 s26, v131
	s_lshr_b32 s27, s4, 13
	s_add_u32 s25, s6, s26
	s_cmpk_ge_u32 s25, 2784
	s_cbranch_scc1 .Lipe0_done
	s_cmpk_ge_u32 s25, 1760
	s_cbranch_scc1 .Lipe0_gate
	s_cmpk_ge_u32 s25, 1632
	s_cbranch_scc1 .Lipe0_sv
	s_cmpk_ge_u32 s25, 1504
	s_cbranch_scc1 .Lipe0_sk
	s_cmpk_ge_u32 s25, 1120
	s_cbranch_scc1 .Lipe0_sq
	s_cmpk_ge_u32 s25, 864
	s_cbranch_scc1 .Lipe0_dv
	s_cmpk_ge_u32 s25, 608
	s_cbranch_scc1 .Lipe0_dk
	s_cmpk_ge_u32 s25, 352
	s_cbranch_scc1 .Lipe0_dq
	s_mul_i32 s10, s4, 0x15c0
	s_lshl_b32 s11, s25, 1
	s_add_u32 s10, s10, s11
	s_add_u32 s8, s50, s10
	s_addc_u32 s9, s51, 0
	v_cvt_pk_bf16_f32 v136, v126, v127
	v_cvt_pk_bf16_f32 v137, v128, v129
	v_cvt_pk_bf16_f32 v138, v94, v95
	v_cvt_pk_bf16_f32 v139, v96, v97
	s_nop 0
	v_permlane32_swap_b32_e32 v136, v138
	v_permlane32_swap_b32_e32 v137, v139
	s_nop 0
	v_permlane16_swap_b32_e32 v136, v138
	v_permlane16_swap_b32_e32 v137, v139
	global_store_dwordx4 v132, v[136:139], s[8:9] nt
	s_nop 1
	v_cvt_pk_bf16_f32 v136, v122, v123
	v_cvt_pk_bf16_f32 v137, v124, v125
	v_cvt_pk_bf16_f32 v138, v90, v91
	v_cvt_pk_bf16_f32 v139, v92, v93
	s_nop 0
	v_permlane32_swap_b32_e32 v136, v138
	v_permlane32_swap_b32_e32 v137, v139
	s_nop 0
	v_permlane16_swap_b32_e32 v136, v138
	v_permlane16_swap_b32_e32 v137, v139
	v_add_u32_e32 v134, 0x15c00, v132
	global_store_dwordx4 v134, v[136:139], s[8:9] nt
	s_nop 1
	v_cvt_pk_bf16_f32 v136, v118, v119
	v_cvt_pk_bf16_f32 v137, v120, v121
	v_cvt_pk_bf16_f32 v138, v86, v87
	v_cvt_pk_bf16_f32 v139, v88, v89
	s_nop 0
	v_permlane32_swap_b32_e32 v136, v138
	v_permlane32_swap_b32_e32 v137, v139
	s_nop 0
	v_permlane16_swap_b32_e32 v136, v138
	v_permlane16_swap_b32_e32 v137, v139
	v_add_u32_e32 v134, 0x2b800, v132
	global_store_dwordx4 v134, v[136:139], s[8:9] nt
	s_nop 1
	v_cvt_pk_bf16_f32 v136, v114, v115
	v_cvt_pk_bf16_f32 v137, v116, v117
	v_cvt_pk_bf16_f32 v138, v82, v83
	v_cvt_pk_bf16_f32 v139, v84, v85
	s_nop 0
	v_permlane32_swap_b32_e32 v136, v138
	v_permlane32_swap_b32_e32 v137, v139
	s_nop 0
	v_permlane16_swap_b32_e32 v136, v138
	v_permlane16_swap_b32_e32 v137, v139
	v_add_u32_e32 v134, 0x41400, v132
	global_store_dwordx4 v134, v[136:139], s[8:9] nt
	s_nop 1
	v_cvt_pk_bf16_f32 v136, v110, v111
	v_cvt_pk_bf16_f32 v137, v112, v113
	v_cvt_pk_bf16_f32 v138, v78, v79
	v_cvt_pk_bf16_f32 v139, v80, v81
	s_nop 0
	v_permlane32_swap_b32_e32 v136, v138
	v_permlane32_swap_b32_e32 v137, v139
	s_nop 0
	v_permlane16_swap_b32_e32 v136, v138
	v_permlane16_swap_b32_e32 v137, v139
	v_add_u32_e32 v134, 0xae000, v132
	global_store_dwordx4 v134, v[136:139], s[8:9] nt
	s_nop 1
	v_cvt_pk_bf16_f32 v136, v106, v107
	v_cvt_pk_bf16_f32 v137, v108, v109
	v_cvt_pk_bf16_f32 v138, v74, v75
	v_cvt_pk_bf16_f32 v139, v76, v77
	s_nop 0
	v_permlane32_swap_b32_e32 v136, v138
	v_permlane32_swap_b32_e32 v137, v139
	s_nop 0
	v_permlane16_swap_b32_e32 v136, v138
	v_permlane16_swap_b32_e32 v137, v139
	v_add_u32_e32 v134, 0xc3c00, v132
	global_store_dwordx4 v134, v[136:139], s[8:9] nt
	s_nop 1
	v_cvt_pk_bf16_f32 v136, v102, v103
	v_cvt_pk_bf16_f32 v137, v104, v105
	v_cvt_pk_bf16_f32 v138, v70, v71
	v_cvt_pk_bf16_f32 v139, v72, v73
	s_nop 0
	v_permlane32_swap_b32_e32 v136, v138
	v_permlane32_swap_b32_e32 v137, v139
	s_nop 0
	v_permlane16_swap_b32_e32 v136, v138
	v_permlane16_swap_b32_e32 v137, v139
	v_add_u32_e32 v134, 0xd9800, v132
	global_store_dwordx4 v134, v[136:139], s[8:9] nt
	s_nop 1
	v_cvt_pk_bf16_f32 v136, v98, v99
	v_cvt_pk_bf16_f32 v137, v100, v101
	v_cvt_pk_bf16_f32 v138, v66, v67
	v_cvt_pk_bf16_f32 v139, v68, v69
	s_nop 0
	v_permlane32_swap_b32_e32 v136, v138
	v_permlane32_swap_b32_e32 v137, v139
	s_nop 0
	v_permlane16_swap_b32_e32 v136, v138
	v_permlane16_swap_b32_e32 v137, v139
	v_add_u32_e32 v134, 0xef400, v132
	global_store_dwordx4 v134, v[136:139], s[8:9] nt
	s_nop 1
	s_branch .Lipe0_done

; DI u16 f2bf(float x) { unsigned u = __float_as_uint(x); u += 0x7fffu + ((u >> 16) & 1u); return (u16)(u >> 16); }
; DI void phase_inproj(const Params& p, int layer, char* lds) {
;     ...
;         if (cw < DIN) {
;           float sc = 1.f;
;           if (col >= C_DQ && col < C_DK) sc = SC_DQ;
;           if (col >= C_SQ && col < C_SK) sc = SC_SQ;
;           const bool gate = col >= C_GATE;
; #pragma unroll
;           for (int ai = 0; ai < 2; ++ai)
; #pragma unroll
;             for (int m = 0; m < 4; ++m) {
; #pragma unroll
;               for (int j = 0; j < 4; ++j) {
;                 const int row = m0 + ai * 128 + wr8 * 64 + m * 16 + fq * 4 + j;
;                 float v = acc[ai][bj][m][n][j] * sc;
;                 if (gate) v = v * __builtin_amdgcn_rcpf(1.f + __expf(-v));
;                 dst[(size_t)row * dstr + fr] = f2bf(v);
;               }
.Lipe0_scaled:
	s_mul_i32 s10, s4, 0x15c0
	s_lshl_b32 s11, s25, 1
	s_add_u32 s10, s10, s11
	s_add_u32 s8, s50, s10
	s_addc_u32 s9, s51, 0
	v_mul_f32_e32 v126, v146, v126
	v_mul_f32_e32 v127, v146, v127
	v_mul_f32_e32 v128, v146, v128
	v_mul_f32_e32 v129, v146, v129
	v_mul_f32_e32 v94, v146, v94
	v_mul_f32_e32 v95, v146, v95
	v_mul_f32_e32 v96, v146, v96
	v_mul_f32_e32 v97, v146, v97
	v_cvt_pk_bf16_f32 v136, v126, v127
	v_cvt_pk_bf16_f32 v137, v128, v129
	v_cvt_pk_bf16_f32 v138, v94, v95
	v_cvt_pk_bf16_f32 v139, v96, v97
	s_nop 0
	v_permlane32_swap_b32_e32 v136, v138
	v_permlane32_swap_b32_e32 v137, v139
	s_nop 0
	v_permlane16_swap_b32_e32 v136, v138
	v_permlane16_swap_b32_e32 v137, v139
	global_store_dwordx4 v132, v[136:139], s[8:9] nt
	s_nop 1
	v_mul_f32_e32 v122, v146, v122
	v_mul_f32_e32 v123, v146, v123
	v_mul_f32_e32 v124, v146, v124
	v_mul_f32_e32 v125, v146, v125
	v_mul_f32_e32 v90, v146, v90
	v_mul_f32_e32 v91, v146, v91
	v_mul_f32_e32 v92, v146, v92
	v_mul_f32_e32 v93, v146, v93
	v_cvt_pk_bf16_f32 v136, v122, v123
	v_cvt_pk_bf16_f32 v137, v124, v125
	v_cvt_pk_bf16_f32 v138, v90, v91
	v_cvt_pk_bf16_f32 v139, v92, v93
	s_nop 0
	v_permlane32_swap_b32_e32 v136, v138
	v_permlane32_swap_b32_e32 v137, v139
	s_nop 0
	v_permlane16_swap_b32_e32 v136, v138
	v_permlane16_swap_b32_e32 v137, v139
	v_add_u32_e32 v134, 0x15c00, v132
	global_store_dwordx4 v134, v[136:139], s[8:9] nt
	s_nop 1
	v_mul_f32_e32 v118, v146, v118
	v_mul_f32_e32 v119, v146, v119
	v_mul_f32_e32 v120, v146, v120
	v_mul_f32_e32 v121, v146, v121
	v_mul_f32_e32 v86, v146, v86
	v_mul_f32_e32 v87, v146, v87
	v_mul_f32_e32 v88, v146, v88
	v_mul_f32_e32 v89, v146, v89
	v_cvt_pk_bf16_f32 v136, v118, v119
	v_cvt_pk_bf16_f32 v137, v120, v121
	v_cvt_pk_bf16_f32 v138, v86, v87
	v_cvt_pk_bf16_f32 v139, v88, v89
	s_nop 0
	v_permlane32_swap_b32_e32 v136, v138
	v_permlane32_swap_b32_e32 v137, v139
	s_nop 0
	v_permlane16_swap_b32_e32 v136, v138
	v_permlane16_swap_b32_e32 v137, v139
	v_add_u32_e32 v134, 0x2b800, v132
	global_store_dwordx4 v134, v[136:139], s[8:9] nt
	s_nop 1
	v_mul_f32_e32 v114, v146, v114
	v_mul_f32_e32 v115, v146, v115
	v_mul_f32_e32 v116, v146, v116
	v_mul_f32_e32 v117, v146, v117
	v_mul_f32_e32 v82, v146, v82
	v_mul_f32_e32 v83, v146, v83
	v_mul_f32_e32 v84, v146, v84
	v_mul_f32_e32 v85, v146, v85
	v_cvt_pk_bf16_f32 v136, v114, v115
	v_cvt_pk_bf16_f32 v137, v116, v117
	v_cvt_pk_bf16_f32 v138, v82, v83
	v_cvt_pk_bf16_f32 v139, v84, v85
	s_nop 0
	v_permlane32_swap_b32_e32 v136, v138
	v_permlane32_swap_b32_e32 v137, v139
	s_nop 0
	v_permlane16_swap_b32_e32 v136, v138
	v_permlane16_swap_b32_e32 v137, v139
	v_add_u32_e32 v134, 0x41400, v132
	global_store_dwordx4 v134, v[136:139], s[8:9] nt
	s_nop 1
	v_mul_f32_e32 v110, v146, v110
	v_mul_f32_e32 v111, v146, v111
	v_mul_f32_e32 v112, v146, v112
	v_mul_f32_e32 v113, v146, v113
	v_mul_f32_e32 v78, v146, v78
	v_mul_f32_e32 v79, v146, v79
	v_mul_f32_e32 v80, v146, v80
	v_mul_f32_e32 v81, v146, v81
	v_cvt_pk_bf16_f32 v136, v110, v111
	v_cvt_pk_bf16_f32 v137, v112, v113
	v_cvt_pk_bf16_f32 v138, v78, v79
	v_cvt_pk_bf16_f32 v139, v80, v81
	s_nop 0
	v_permlane32_swap_b32_e32 v136, v138
	v_permlane32_swap_b32_e32 v137, v139
	s_nop 0
	v_permlane16_swap_b32_e32 v136, v138
	v_permlane16_swap_b32_e32 v137, v139
	v_add_u32_e32 v134, 0xae000, v132
	global_store_dwordx4 v134, v[136:139], s[8:9] nt
	s_nop 1
	v_mul_f32_e32 v106, v146, v106
	v_mul_f32_e32 v107, v146, v107
	v_mul_f32_e32 v108, v146, v108
	v_mul_f32_e32 v109, v146, v109
	v_mul_f32_e32 v74, v146, v74
	v_mul_f32_e32 v75, v146, v75
	v_mul_f32_e32 v76, v146, v76
	v_mul_f32_e32 v77, v146, v77
	v_cvt_pk_bf16_f32 v136, v106, v107
	v_cvt_pk_bf16_f32 v137, v108, v109
	v_cvt_pk_bf16_f32 v138, v74, v75
	v_cvt_pk_bf16_f32 v139, v76, v77
	s_nop 0
	v_permlane32_swap_b32_e32 v136, v138
	v_permlane32_swap_b32_e32 v137, v139
	s_nop 0
	v_permlane16_swap_b32_e32 v136, v138
	v_permlane16_swap_b32_e32 v137, v139
	v_add_u32_e32 v134, 0xc3c00, v132
	global_store_dwordx4 v134, v[136:139], s[8:9] nt
	s_nop 1
	v_mul_f32_e32 v102, v146, v102
	v_mul_f32_e32 v103, v146, v103
	v_mul_f32_e32 v104, v146, v104
	v_mul_f32_e32 v105, v146, v105
	v_mul_f32_e32 v70, v146, v70
	v_mul_f32_e32 v71, v146, v71
	v_mul_f32_e32 v72, v146, v72
	v_mul_f32_e32 v73, v146, v73
	v_cvt_pk_bf16_f32 v136, v102, v103
	v_cvt_pk_bf16_f32 v137, v104, v105
	v_cvt_pk_bf16_f32 v138, v70, v71
	v_cvt_pk_bf16_f32 v139, v72, v73
	s_nop 0
	v_permlane32_swap_b32_e32 v136, v138
	v_permlane32_swap_b32_e32 v137, v139
	s_nop 0
	v_permlane16_swap_b32_e32 v136, v138
	v_permlane16_swap_b32_e32 v137, v139
	v_add_u32_e32 v134, 0xd9800, v132
	global_store_dwordx4 v134, v[136:139], s[8:9] nt
	s_nop 1
	v_mul_f32_e32 v98, v146, v98
	v_mul_f32_e32 v99, v146, v99
	v_mul_f32_e32 v100, v146, v100
	v_mul_f32_e32 v101, v146, v101
	v_mul_f32_e32 v66, v146, v66
	v_mul_f32_e32 v67, v146, v67
	v_mul_f32_e32 v68, v146, v68
	v_mul_f32_e32 v69, v146, v69
	v_cvt_pk_bf16_f32 v136, v98, v99
	v_cvt_pk_bf16_f32 v137, v100, v101
	v_cvt_pk_bf16_f32 v138, v66, v67
	v_cvt_pk_bf16_f32 v139, v68, v69
	s_nop 0
	v_permlane32_swap_b32_e32 v136, v138
	v_permlane32_swap_b32_e32 v137, v139
	s_nop 0
	v_permlane16_swap_b32_e32 v136, v138
	v_permlane16_swap_b32_e32 v137, v139
	v_add_u32_e32 v134, 0xef400, v132
	global_store_dwordx4 v134, v[136:139], s[8:9] nt
	s_nop 1
	s_branch .Lipe0_done
; DI u16 f2bf(float x) { unsigned u = __float_as_uint(x); u += 0x7fffu + ((u >> 16) & 1u); return (u16)(u >> 16); }
; DI void phase_inproj(const Params& p, int layer, char* lds) {
;     ...
;           const bool gate = col >= C_GATE;
; #pragma unroll
;           for (int ai = 0; ai < 2; ++ai)
; #pragma unroll
;             for (int m = 0; m < 4; ++m) {
; #pragma unroll
;               for (int j = 0; j < 4; ++j) {
;                 const int row = m0 + ai * 128 + wr8 * 64 + m * 16 + fq * 4 + j;
;                 float v = acc[ai][bj][m][n][j] * sc;
;                 if (gate) v = v * __builtin_amdgcn_rcpf(1.f + __expf(-v));
;                 dst[(size_t)row * dstr + fr] = f2bf(v);
.Lipe0_gate:
	s_mul_i32 s10, s4, 0x15c0
	s_lshl_b32 s11, s25, 1
	s_add_u32 s10, s10, s11
	s_add_u32 s8, s50, s10
	s_addc_u32 s9, s51, 0
	v_mul_f32_e32 v140, 0xbfb8aa3b, v126
	v_mul_f32_e32 v141, 0xbfb8aa3b, v127
	v_mul_f32_e32 v142, 0xbfb8aa3b, v128
	v_mul_f32_e32 v143, 0xbfb8aa3b, v129
	v_exp_f32_e32 v140, v140
	v_exp_f32_e32 v141, v141
	v_exp_f32_e32 v142, v142
	v_exp_f32_e32 v143, v143
	v_add_f32_e32 v140, 1.0, v140
	v_add_f32_e32 v141, 1.0, v141
	v_add_f32_e32 v142, 1.0, v142
	v_add_f32_e32 v143, 1.0, v143
	v_rcp_f32_e32 v140, v140
	v_rcp_f32_e32 v141, v141
	v_rcp_f32_e32 v142, v142
	v_rcp_f32_e32 v143, v143
	v_mul_f32_e32 v126, v126, v140
	v_mul_f32_e32 v127, v127, v141
	v_mul_f32_e32 v128, v128, v142
	v_mul_f32_e32 v129, v129, v143
	v_mul_f32_e32 v140, 0xbfb8aa3b, v94
	v_mul_f32_e32 v141, 0xbfb8aa3b, v95
	v_mul_f32_e32 v142, 0xbfb8aa3b, v96
	v_mul_f32_e32 v143, 0xbfb8aa3b, v97
	v_exp_f32_e32 v140, v140
	v_exp_f32_e32 v141, v141
	v_exp_f32_e32 v142, v142
	v_exp_f32_e32 v143, v143
	v_add_f32_e32 v140, 1.0, v140
	v_add_f32_e32 v141, 1.0, v141
	v_add_f32_e32 v142, 1.0, v142
	v_add_f32_e32 v143, 1.0, v143
	v_rcp_f32_e32 v140, v140
	v_rcp_f32_e32 v141, v141
	v_rcp_f32_e32 v142, v142
	v_rcp_f32_e32 v143, v143
	v_mul_f32_e32 v94, v94, v140
	v_mul_f32_e32 v95, v95, v141
	v_mul_f32_e32 v96, v96, v142
	v_mul_f32_e32 v97, v97, v143
	v_cvt_pk_bf16_f32 v136, v126, v127
	v_cvt_pk_bf16_f32 v137, v128, v129
	v_cvt_pk_bf16_f32 v138, v94, v95
	v_cvt_pk_bf16_f32 v139, v96, v97
	s_nop 0
	v_permlane32_swap_b32_e32 v136, v138
	v_permlane32_swap_b32_e32 v137, v139
	s_nop 0
	v_permlane16_swap_b32_e32 v136, v138
	v_permlane16_swap_b32_e32 v137, v139
	global_store_dwordx4 v132, v[136:139], s[8:9] nt
	s_nop 1
	v_mul_f32_e32 v140, 0xbfb8aa3b, v122
	v_mul_f32_e32 v141, 0xbfb8aa3b, v123
	v_mul_f32_e32 v142, 0xbfb8aa3b, v124
	v_mul_f32_e32 v143, 0xbfb8aa3b, v125
	v_exp_f32_e32 v140, v140
	v_exp_f32_e32 v141, v141
	v_exp_f32_e32 v142, v142
	v_exp_f32_e32 v143, v143
	v_add_f32_e32 v140, 1.0, v140
	v_add_f32_e32 v141, 1.0, v141
	v_add_f32_e32 v142, 1.0, v142
	v_add_f32_e32 v143, 1.0, v143
	v_rcp_f32_e32 v140, v140
	v_rcp_f32_e32 v141, v141
	v_rcp_f32_e32 v142, v142
	v_rcp_f32_e32 v143, v143
	v_mul_f32_e32 v122, v122, v140
	v_mul_f32_e32 v123, v123, v141
	v_mul_f32_e32 v124, v124, v142
	v_mul_f32_e32 v125, v125, v143
	v_mul_f32_e32 v140, 0xbfb8aa3b, v90
	v_mul_f32_e32 v141, 0xbfb8aa3b, v91
	v_mul_f32_e32 v142, 0xbfb8aa3b, v92
	v_mul_f32_e32 v143, 0xbfb8aa3b, v93
	v_exp_f32_e32 v140, v140
	v_exp_f32_e32 v141, v141
	v_exp_f32_e32 v142, v142
	v_exp_f32_e32 v143, v143
	v_add_f32_e32 v140, 1.0, v140
	v_add_f32_e32 v141, 1.0, v141
	v_add_f32_e32 v142, 1.0, v142
	v_add_f32_e32 v143, 1.0, v143
	v_rcp_f32_e32 v140, v140
	v_rcp_f32_e32 v141, v141
	v_rcp_f32_e32 v142, v142
	v_rcp_f32_e32 v143, v143
	v_mul_f32_e32 v90, v90, v140
	v_mul_f32_e32 v91, v91, v141
	v_mul_f32_e32 v92, v92, v142
	v_mul_f32_e32 v93, v93, v143
	v_cvt_pk_bf16_f32 v136, v122, v123
	v_cvt_pk_bf16_f32 v137, v124, v125
	v_cvt_pk_bf16_f32 v138, v90, v91
	v_cvt_pk_bf16_f32 v139, v92, v93
	s_nop 0
	v_permlane32_swap_b32_e32 v136, v138
	v_permlane32_swap_b32_e32 v137, v139
	s_nop 0
	v_permlane16_swap_b32_e32 v136, v138
	v_permlane16_swap_b32_e32 v137, v139
	v_add_u32_e32 v134, 0x15c00, v132
	global_store_dwordx4 v134, v[136:139], s[8:9] nt
	s_nop 1
	v_mul_f32_e32 v140, 0xbfb8aa3b, v118
	v_mul_f32_e32 v141, 0xbfb8aa3b, v119
	v_mul_f32_e32 v142, 0xbfb8aa3b, v120
	v_mul_f32_e32 v143, 0xbfb8aa3b, v121
	v_exp_f32_e32 v140, v140
	v_exp_f32_e32 v141, v141
	v_exp_f32_e32 v142, v142
	v_exp_f32_e32 v143, v143
	v_add_f32_e32 v140, 1.0, v140
	v_add_f32_e32 v141, 1.0, v141
	v_add_f32_e32 v142, 1.0, v142
	v_add_f32_e32 v143, 1.0, v143
	v_rcp_f32_e32 v140, v140
	v_rcp_f32_e32 v141, v141
	v_rcp_f32_e32 v142, v142
	v_rcp_f32_e32 v143, v143
	v_mul_f32_e32 v118, v118, v140
	v_mul_f32_e32 v119, v119, v141
	v_mul_f32_e32 v120, v120, v142
	v_mul_f32_e32 v121, v121, v143
	v_mul_f32_e32 v140, 0xbfb8aa3b, v86
	v_mul_f32_e32 v141, 0xbfb8aa3b, v87
	v_mul_f32_e32 v142, 0xbfb8aa3b, v88
	v_mul_f32_e32 v143, 0xbfb8aa3b, v89
	v_exp_f32_e32 v140, v140
	v_exp_f32_e32 v141, v141
	v_exp_f32_e32 v142, v142
	v_exp_f32_e32 v143, v143
	v_add_f32_e32 v140, 1.0, v140
	v_add_f32_e32 v141, 1.0, v141
	v_add_f32_e32 v142, 1.0, v142
	v_add_f32_e32 v143, 1.0, v143
	v_rcp_f32_e32 v140, v140
	v_rcp_f32_e32 v141, v141
	v_rcp_f32_e32 v142, v142
	v_rcp_f32_e32 v143, v143
	v_mul_f32_e32 v86, v86, v140
	v_mul_f32_e32 v87, v87, v141
	v_mul_f32_e32 v88, v88, v142
	v_mul_f32_e32 v89, v89, v143
	v_cvt_pk_bf16_f32 v136, v118, v119
	v_cvt_pk_bf16_f32 v137, v120, v121
	v_cvt_pk_bf16_f32 v138, v86, v87
	v_cvt_pk_bf16_f32 v139, v88, v89
	s_nop 0
	v_permlane32_swap_b32_e32 v136, v138
	v_permlane32_swap_b32_e32 v137, v139
	s_nop 0
	v_permlane16_swap_b32_e32 v136, v138
	v_permlane16_swap_b32_e32 v137, v139
	v_add_u32_e32 v134, 0x2b800, v132
	global_store_dwordx4 v134, v[136:139], s[8:9] nt
	s_nop 1
	v_mul_f32_e32 v140, 0xbfb8aa3b, v114
	v_mul_f32_e32 v141, 0xbfb8aa3b, v115
	v_mul_f32_e32 v142, 0xbfb8aa3b, v116
	v_mul_f32_e32 v143, 0xbfb8aa3b, v117
	v_exp_f32_e32 v140, v140
	v_exp_f32_e32 v141, v141
	v_exp_f32_e32 v142, v142
	v_exp_f32_e32 v143, v143
	v_add_f32_e32 v140, 1.0, v140
	v_add_f32_e32 v141, 1.0, v141
	v_add_f32_e32 v142, 1.0, v142
	v_add_f32_e32 v143, 1.0, v143
	v_rcp_f32_e32 v140, v140
	v_rcp_f32_e32 v141, v141
	v_rcp_f32_e32 v142, v142
	v_rcp_f32_e32 v143, v143
	v_mul_f32_e32 v114, v114, v140
	v_mul_f32_e32 v115, v115, v141
	v_mul_f32_e32 v116, v116, v142
	v_mul_f32_e32 v117, v117, v143
	v_mul_f32_e32 v140, 0xbfb8aa3b, v82
	v_mul_f32_e32 v141, 0xbfb8aa3b, v83
; DI u16 f2bf(float x) { unsigned u = __float_as_uint(x); u += 0x7fffu + ((u >> 16) & 1u); return (u16)(u >> 16); }
; DI void phase_inproj(const Params& p, int layer, char* lds) {
;     ...
;           const bool gate = col >= C_GATE;
; #pragma unroll
;           for (int ai = 0; ai < 2; ++ai)
; #pragma unroll
;             for (int m = 0; m < 4; ++m) {
; #pragma unroll
;               for (int j = 0; j < 4; ++j) {
;                 const int row = m0 + ai * 128 + wr8 * 64 + m * 16 + fq * 4 + j;
;                 float v = acc[ai][bj][m][n][j] * sc;
;                 if (gate) v = v * __builtin_amdgcn_rcpf(1.f + __expf(-v));
;                 dst[(size_t)row * dstr + fr] = f2bf(v);
	v_mul_f32_e32 v142, 0xbfb8aa3b, v84
	v_mul_f32_e32 v143, 0xbfb8aa3b, v85
	v_exp_f32_e32 v140, v140
	v_exp_f32_e32 v141, v141
	v_exp_f32_e32 v142, v142
	v_exp_f32_e32 v143, v143
	v_add_f32_e32 v140, 1.0, v140
	v_add_f32_e32 v141, 1.0, v141
	v_add_f32_e32 v142, 1.0, v142
	v_add_f32_e32 v143, 1.0, v143
	v_rcp_f32_e32 v140, v140
	v_rcp_f32_e32 v141, v141
	v_rcp_f32_e32 v142, v142
	v_rcp_f32_e32 v143, v143
	v_mul_f32_e32 v82, v82, v140
	v_mul_f32_e32 v83, v83, v141
	v_mul_f32_e32 v84, v84, v142
	v_mul_f32_e32 v85, v85, v143
	v_cvt_pk_bf16_f32 v136, v114, v115
	v_cvt_pk_bf16_f32 v137, v116, v117
	v_cvt_pk_bf16_f32 v138, v82, v83
	v_cvt_pk_bf16_f32 v139, v84, v85
	s_nop 0
	v_permlane32_swap_b32_e32 v136, v138
	v_permlane32_swap_b32_e32 v137, v139
	s_nop 0
	v_permlane16_swap_b32_e32 v136, v138
	v_permlane16_swap_b32_e32 v137, v139
	v_add_u32_e32 v134, 0x41400, v132
	global_store_dwordx4 v134, v[136:139], s[8:9] nt
	s_nop 1
	v_mul_f32_e32 v140, 0xbfb8aa3b, v110
	v_mul_f32_e32 v141, 0xbfb8aa3b, v111
	v_mul_f32_e32 v142, 0xbfb8aa3b, v112
	v_mul_f32_e32 v143, 0xbfb8aa3b, v113
	v_exp_f32_e32 v140, v140
	v_exp_f32_e32 v141, v141
	v_exp_f32_e32 v142, v142
	v_exp_f32_e32 v143, v143
	v_add_f32_e32 v140, 1.0, v140
	v_add_f32_e32 v141, 1.0, v141
	v_add_f32_e32 v142, 1.0, v142
	v_add_f32_e32 v143, 1.0, v143
	v_rcp_f32_e32 v140, v140
	v_rcp_f32_e32 v141, v141
	v_rcp_f32_e32 v142, v142
	v_rcp_f32_e32 v143, v143
	v_mul_f32_e32 v110, v110, v140
	v_mul_f32_e32 v111, v111, v141
	v_mul_f32_e32 v112, v112, v142
	v_mul_f32_e32 v113, v113, v143
	v_mul_f32_e32 v140, 0xbfb8aa3b, v78
	v_mul_f32_e32 v141, 0xbfb8aa3b, v79
	v_mul_f32_e32 v142, 0xbfb8aa3b, v80
	v_mul_f32_e32 v143, 0xbfb8aa3b, v81
	v_exp_f32_e32 v140, v140
	v_exp_f32_e32 v141, v141
	v_exp_f32_e32 v142, v142
	v_exp_f32_e32 v143, v143
	v_add_f32_e32 v140, 1.0, v140
	v_add_f32_e32 v141, 1.0, v141
	v_add_f32_e32 v142, 1.0, v142
	v_add_f32_e32 v143, 1.0, v143
	v_rcp_f32_e32 v140, v140
	v_rcp_f32_e32 v141, v141
	v_rcp_f32_e32 v142, v142
	v_rcp_f32_e32 v143, v143
	v_mul_f32_e32 v78, v78, v140
	v_mul_f32_e32 v79, v79, v141
	v_mul_f32_e32 v80, v80, v142
	v_mul_f32_e32 v81, v81, v143
	v_cvt_pk_bf16_f32 v136, v110, v111
	v_cvt_pk_bf16_f32 v137, v112, v113
	v_cvt_pk_bf16_f32 v138, v78, v79
	v_cvt_pk_bf16_f32 v139, v80, v81
	s_nop 0
	v_permlane32_swap_b32_e32 v136, v138
	v_permlane32_swap_b32_e32 v137, v139
	s_nop 0
	v_permlane16_swap_b32_e32 v136, v138
	v_permlane16_swap_b32_e32 v137, v139
	v_add_u32_e32 v134, 0xae000, v132
	global_store_dwordx4 v134, v[136:139], s[8:9] nt
	s_nop 1
	v_mul_f32_e32 v140, 0xbfb8aa3b, v106
	v_mul_f32_e32 v141, 0xbfb8aa3b, v107
	v_mul_f32_e32 v142, 0xbfb8aa3b, v108
	v_mul_f32_e32 v143, 0xbfb8aa3b, v109
	v_exp_f32_e32 v140, v140
	v_exp_f32_e32 v141, v141
	v_exp_f32_e32 v142, v142
	v_exp_f32_e32 v143, v143
	v_add_f32_e32 v140, 1.0, v140
	v_add_f32_e32 v141, 1.0, v141
	v_add_f32_e32 v142, 1.0, v142
	v_add_f32_e32 v143, 1.0, v143
	v_rcp_f32_e32 v140, v140
	v_rcp_f32_e32 v141, v141
	v_rcp_f32_e32 v142, v142
	v_rcp_f32_e32 v143, v143
	v_mul_f32_e32 v106, v106, v140
	v_mul_f32_e32 v107, v107, v141
	v_mul_f32_e32 v108, v108, v142
	v_mul_f32_e32 v109, v109, v143
	v_mul_f32_e32 v140, 0xbfb8aa3b, v74
	v_mul_f32_e32 v141, 0xbfb8aa3b, v75
	v_mul_f32_e32 v142, 0xbfb8aa3b, v76
	v_mul_f32_e32 v143, 0xbfb8aa3b, v77
	v_exp_f32_e32 v140, v140
	v_exp_f32_e32 v141, v141
	v_exp_f32_e32 v142, v142
	v_exp_f32_e32 v143, v143
	v_add_f32_e32 v140, 1.0, v140
	v_add_f32_e32 v141, 1.0, v141
	v_add_f32_e32 v142, 1.0, v142
	v_add_f32_e32 v143, 1.0, v143
	v_rcp_f32_e32 v140, v140
	v_rcp_f32_e32 v141, v141
	v_rcp_f32_e32 v142, v142
	v_rcp_f32_e32 v143, v143
	v_mul_f32_e32 v74, v74, v140
	v_mul_f32_e32 v75, v75, v141
; DI u16 f2bf(float x) { unsigned u = __float_as_uint(x); u += 0x7fffu + ((u >> 16) & 1u); return (u16)(u >> 16); }
; DI void phase_inproj(const Params& p, int layer, char* lds) {
;     ...
;           const bool gate = col >= C_GATE;
; #pragma unroll
;           for (int ai = 0; ai < 2; ++ai)
; #pragma unroll
;             for (int m = 0; m < 4; ++m) {
; #pragma unroll
;               for (int j = 0; j < 4; ++j) {
;                 const int row = m0 + ai * 128 + wr8 * 64 + m * 16 + fq * 4 + j;
;                 float v = acc[ai][bj][m][n][j] * sc;
;                 if (gate) v = v * __builtin_amdgcn_rcpf(1.f + __expf(-v));
;                 dst[(size_t)row * dstr + fr] = f2bf(v);
	v_mul_f32_e32 v76, v76, v142
	v_mul_f32_e32 v77, v77, v143
	v_cvt_pk_bf16_f32 v136, v106, v107
	v_cvt_pk_bf16_f32 v137, v108, v109
	v_cvt_pk_bf16_f32 v138, v74, v75
	v_cvt_pk_bf16_f32 v139, v76, v77
	s_nop 0
	v_permlane32_swap_b32_e32 v136, v138
	v_permlane32_swap_b32_e32 v137, v139
	s_nop 0
	v_permlane16_swap_b32_e32 v136, v138
	v_permlane16_swap_b32_e32 v137, v139
	v_add_u32_e32 v134, 0xc3c00, v132
	global_store_dwordx4 v134, v[136:139], s[8:9] nt
	s_nop 1
	v_mul_f32_e32 v140, 0xbfb8aa3b, v102
	v_mul_f32_e32 v141, 0xbfb8aa3b, v103
	v_mul_f32_e32 v142, 0xbfb8aa3b, v104
	v_mul_f32_e32 v143, 0xbfb8aa3b, v105
	v_exp_f32_e32 v140, v140
	v_exp_f32_e32 v141, v141
	v_exp_f32_e32 v142, v142
	v_exp_f32_e32 v143, v143
	v_add_f32_e32 v140, 1.0, v140
	v_add_f32_e32 v141, 1.0, v141
	v_add_f32_e32 v142, 1.0, v142
	v_add_f32_e32 v143, 1.0, v143
	v_rcp_f32_e32 v140, v140
	v_rcp_f32_e32 v141, v141
	v_rcp_f32_e32 v142, v142
	v_rcp_f32_e32 v143, v143
	v_mul_f32_e32 v102, v102, v140
	v_mul_f32_e32 v103, v103, v141
	v_mul_f32_e32 v104, v104, v142
	v_mul_f32_e32 v105, v105, v143
	v_mul_f32_e32 v140, 0xbfb8aa3b, v70
	v_mul_f32_e32 v141, 0xbfb8aa3b, v71
	v_mul_f32_e32 v142, 0xbfb8aa3b, v72
	v_mul_f32_e32 v143, 0xbfb8aa3b, v73
	v_exp_f32_e32 v140, v140
	v_exp_f32_e32 v141, v141
	v_exp_f32_e32 v142, v142
	v_exp_f32_e32 v143, v143
	v_add_f32_e32 v140, 1.0, v140
	v_add_f32_e32 v141, 1.0, v141
	v_add_f32_e32 v142, 1.0, v142
	v_add_f32_e32 v143, 1.0, v143
	v_rcp_f32_e32 v140, v140
	v_rcp_f32_e32 v141, v141
	v_rcp_f32_e32 v142, v142
	v_rcp_f32_e32 v143, v143
	v_mul_f32_e32 v70, v70, v140
	v_mul_f32_e32 v71, v71, v141
	v_mul_f32_e32 v72, v72, v142
	v_mul_f32_e32 v73, v73, v143
	v_cvt_pk_bf16_f32 v136, v102, v103
	v_cvt_pk_bf16_f32 v137, v104, v105
	v_cvt_pk_bf16_f32 v138, v70, v71
	v_cvt_pk_bf16_f32 v139, v72, v73
	s_nop 0
	v_permlane32_swap_b32_e32 v136, v138
	v_permlane32_swap_b32_e32 v137, v139
	s_nop 0
	v_permlane16_swap_b32_e32 v136, v138
	v_permlane16_swap_b32_e32 v137, v139
	v_add_u32_e32 v134, 0xd9800, v132
	global_store_dwordx4 v134, v[136:139], s[8:9] nt
	s_nop 1
	v_mul_f32_e32 v140, 0xbfb8aa3b, v98
	v_mul_f32_e32 v141, 0xbfb8aa3b, v99
	v_mul_f32_e32 v142, 0xbfb8aa3b, v100
	v_mul_f32_e32 v143, 0xbfb8aa3b, v101
	v_exp_f32_e32 v140, v140
	v_exp_f32_e32 v141, v141
	v_exp_f32_e32 v142, v142
	v_exp_f32_e32 v143, v143
	v_add_f32_e32 v140, 1.0, v140
	v_add_f32_e32 v141, 1.0, v141
	v_add_f32_e32 v142, 1.0, v142
	v_add_f32_e32 v143, 1.0, v143
	v_rcp_f32_e32 v140, v140
	v_rcp_f32_e32 v141, v141
	v_rcp_f32_e32 v142, v142
	v_rcp_f32_e32 v143, v143
	v_mul_f32_e32 v98, v98, v140
	v_mul_f32_e32 v99, v99, v141
	v_mul_f32_e32 v100, v100, v142
	v_mul_f32_e32 v101, v101, v143
	v_mul_f32_e32 v140, 0xbfb8aa3b, v66
	v_mul_f32_e32 v141, 0xbfb8aa3b, v67
	v_mul_f32_e32 v142, 0xbfb8aa3b, v68
	v_mul_f32_e32 v143, 0xbfb8aa3b, v69
	v_exp_f32_e32 v140, v140
	v_exp_f32_e32 v141, v141
	v_exp_f32_e32 v142, v142
	v_exp_f32_e32 v143, v143
	v_add_f32_e32 v140, 1.0, v140
	v_add_f32_e32 v141, 1.0, v141
	v_add_f32_e32 v142, 1.0, v142
	v_add_f32_e32 v143, 1.0, v143
	v_rcp_f32_e32 v140, v140
	v_rcp_f32_e32 v141, v141
	v_rcp_f32_e32 v142, v142
	v_rcp_f32_e32 v143, v143
	v_mul_f32_e32 v66, v66, v140
	v_mul_f32_e32 v67, v67, v141
	v_mul_f32_e32 v68, v68, v142
	v_mul_f32_e32 v69, v69, v143
	v_cvt_pk_bf16_f32 v136, v98, v99
	v_cvt_pk_bf16_f32 v137, v100, v101
	v_cvt_pk_bf16_f32 v138, v66, v67
	v_cvt_pk_bf16_f32 v139, v68, v69
	s_nop 0
	v_permlane32_swap_b32_e32 v136, v138
	v_permlane32_swap_b32_e32 v137, v139
	s_nop 0
	v_permlane16_swap_b32_e32 v136, v138
	v_permlane16_swap_b32_e32 v137, v139
	v_add_u32_e32 v134, 0xef400, v132
	global_store_dwordx4 v134, v[136:139], s[8:9] nt
	s_nop 1
	s_branch .Lipe0_done

; DI u16 f2bf(float x) { unsigned u = __float_as_uint(x); u += 0x7fffu + ((u >> 16) & 1u); return (u16)(u >> 16); }
; DI void phase_inproj(const Params& p, int layer, char* lds) {
;     ...
;         const int cw = n0 + bj * 128 + wc8 * 32 + n * 16, col = cw + fr;
;         u16* dst = H + cw; int dstr = DIN;
;         {
;           const int bb = m0 / S;
;           if (cw >= C_DK && cw < C_DV) { const int o = cw - C_DK; dst = (u16*)(p.ws + OFF_DK) + ((size_t)(bb * 3 * S + (o >> 6) * S) << 6) + (o & 63); dstr = 64; }
;           else if (cw >= C_DV && cw < C_SQ) { const int o = cw - C_DV; dst = (u16*)(p.ws + OFF_DV) + ((size_t)(bb * 3 * S + (o >> 6) * S) << 6) + (o & 63); dstr = 64; }
;           else if (cw >= C_SK && cw < C_SV) { const int o = cw - C_SK; dst = (u16*)(p.ws + OFF_SK) + ((size_t)(bb * 1 * S + (o >> 6) * S) << 6) + (o & 63); dstr = 64; }
;           else if (cw >= C_SV && cw < C_GATE) { const int o = cw - C_SV; dst = (u16*)(p.ws + OFF_SV) + ((size_t)(bb * 1 * S + (o >> 6) * S) << 6) + (o & 63); dstr = 64; }
;         }
;         if (cw < DIN) {
;           float sc = 1.f;
;           if (col >= C_DQ && col < C_DK) sc = SC_DQ;
;           if (col >= C_SQ && col < C_SK) sc = SC_SQ;
;           const bool gate = col >= C_GATE;
; #pragma unroll
;           for (int ai = 0; ai < 2; ++ai)
; #pragma unroll
;             for (int m = 0; m < 4; ++m) {
; #pragma unroll
;               for (int j = 0; j < 4; ++j) {
;                 const int row = m0 + ai * 128 + wr8 * 64 + m * 16 + fq * 4 + j;
;                 float v = acc[ai][bj][m][n][j] * sc;
;                 if (gate) v = v * __builtin_amdgcn_rcpf(1.f + __expf(-v));
;                 dst[(size_t)row * dstr + fr] = f2bf(v);
;               }
;               __builtin_amdgcn_sched_barrier(0);
;             }
;         }
;       }
.Lipe0_kv:
	v_cvt_pk_bf16_f32 v136, v126, v127
	v_cvt_pk_bf16_f32 v137, v128, v129
	v_cvt_pk_bf16_f32 v138, v94, v95
	v_cvt_pk_bf16_f32 v139, v96, v97
	s_nop 0
	v_permlane32_swap_b32_e32 v136, v138
	v_permlane32_swap_b32_e32 v137, v139
	s_nop 0
	v_permlane16_swap_b32_e32 v136, v138
	v_permlane16_swap_b32_e32 v137, v139
	global_store_dwordx4 v133, v[136:139], s[8:9] nt
	s_nop 1
	v_cvt_pk_bf16_f32 v136, v122, v123
	v_cvt_pk_bf16_f32 v137, v124, v125
	v_cvt_pk_bf16_f32 v138, v90, v91
	v_cvt_pk_bf16_f32 v139, v92, v93
	s_nop 0
	v_permlane32_swap_b32_e32 v136, v138
	v_permlane32_swap_b32_e32 v137, v139
	s_nop 0
	v_permlane16_swap_b32_e32 v136, v138
	v_permlane16_swap_b32_e32 v137, v139
	v_add_u32_e32 v134, 0x800, v133
	global_store_dwordx4 v134, v[136:139], s[8:9] nt
	s_nop 1
	v_cvt_pk_bf16_f32 v136, v118, v119
	v_cvt_pk_bf16_f32 v137, v120, v121
	v_cvt_pk_bf16_f32 v138, v86, v87
	v_cvt_pk_bf16_f32 v139, v88, v89
	s_nop 0
	v_permlane32_swap_b32_e32 v136, v138
	v_permlane32_swap_b32_e32 v137, v139
	s_nop 0
	v_permlane16_swap_b32_e32 v136, v138
	v_permlane16_swap_b32_e32 v137, v139
	v_add_u32_e32 v134, 0x1000, v133
	global_store_dwordx4 v134, v[136:139], s[8:9] nt
	s_nop 1
	v_cvt_pk_bf16_f32 v136, v114, v115
	v_cvt_pk_bf16_f32 v137, v116, v117
	v_cvt_pk_bf16_f32 v138, v82, v83
	v_cvt_pk_bf16_f32 v139, v84, v85
	s_nop 0
	v_permlane32_swap_b32_e32 v136, v138
	v_permlane32_swap_b32_e32 v137, v139
	s_nop 0
	v_permlane16_swap_b32_e32 v136, v138
	v_permlane16_swap_b32_e32 v137, v139
	v_add_u32_e32 v134, 0x1800, v133
	global_store_dwordx4 v134, v[136:139], s[8:9] nt
	s_nop 1
	v_cvt_pk_bf16_f32 v136, v110, v111
	v_cvt_pk_bf16_f32 v137, v112, v113
	v_cvt_pk_bf16_f32 v138, v78, v79
	v_cvt_pk_bf16_f32 v139, v80, v81
	s_nop 0
	v_permlane32_swap_b32_e32 v136, v138
	v_permlane32_swap_b32_e32 v137, v139
	s_nop 0
	v_permlane16_swap_b32_e32 v136, v138
	v_permlane16_swap_b32_e32 v137, v139
	v_add_u32_e32 v134, 0x4000, v133
	global_store_dwordx4 v134, v[136:139], s[8:9] nt
	s_nop 1
	v_cvt_pk_bf16_f32 v136, v106, v107
	v_cvt_pk_bf16_f32 v137, v108, v109
	v_cvt_pk_bf16_f32 v138, v74, v75
	v_cvt_pk_bf16_f32 v139, v76, v77
	s_nop 0
	v_permlane32_swap_b32_e32 v136, v138
	v_permlane32_swap_b32_e32 v137, v139
	s_nop 0
	v_permlane16_swap_b32_e32 v136, v138
	v_permlane16_swap_b32_e32 v137, v139
	v_add_u32_e32 v134, 0x4800, v133
	global_store_dwordx4 v134, v[136:139], s[8:9] nt
	s_nop 1
	v_cvt_pk_bf16_f32 v136, v102, v103
	v_cvt_pk_bf16_f32 v137, v104, v105
	v_cvt_pk_bf16_f32 v138, v70, v71
	v_cvt_pk_bf16_f32 v139, v72, v73
	s_nop 0
	v_permlane32_swap_b32_e32 v136, v138
	v_permlane32_swap_b32_e32 v137, v139
	s_nop 0
	v_permlane16_swap_b32_e32 v136, v138
	v_permlane16_swap_b32_e32 v137, v139
	v_add_u32_e32 v134, 0x5000, v133
	global_store_dwordx4 v134, v[136:139], s[8:9] nt
	s_nop 1
	v_cvt_pk_bf16_f32 v136, v98, v99
	v_cvt_pk_bf16_f32 v137, v100, v101
	v_cvt_pk_bf16_f32 v138, v66, v67
	v_cvt_pk_bf16_f32 v139, v68, v69
	s_nop 0
	v_permlane32_swap_b32_e32 v136, v138
	v_permlane32_swap_b32_e32 v137, v139
	s_nop 0
	v_permlane16_swap_b32_e32 v136, v138
	v_permlane16_swap_b32_e32 v137, v139
	v_add_u32_e32 v134, 0x5800, v133
	global_store_dwordx4 v134, v[136:139], s[8:9] nt
	s_nop 1
.Lipe0_done:
	s_add_u32 s25, s6, s26
	s_add_u32 s25, s25, 128
	s_cmpk_ge_u32 s25, 2784
	s_cbranch_scc1 .Lipe1_done
	s_cmpk_ge_u32 s25, 1760
	s_cbranch_scc1 .Lipe1_gate
	s_cmpk_ge_u32 s25, 1632
	s_cbranch_scc1 .Lipe1_sv
	s_cmpk_ge_u32 s25, 1504
	s_cbranch_scc1 .Lipe1_sk
	s_cmpk_ge_u32 s25, 1120
	s_cbranch_scc1 .Lipe1_sq
	s_cmpk_ge_u32 s25, 864
	s_cbranch_scc1 .Lipe1_dv
	s_cmpk_ge_u32 s25, 608
	s_cbranch_scc1 .Lipe1_dk
	s_cmpk_ge_u32 s25, 352
	s_cbranch_scc1 .Lipe1_dq
	s_mul_i32 s10, s4, 0x15c0
	s_lshl_b32 s11, s25, 1
	s_add_u32 s10, s10, s11
	s_add_u32 s8, s50, s10
	s_addc_u32 s9, s51, 0
	v_cvt_pk_bf16_f32 v136, v62, v63
	v_cvt_pk_bf16_f32 v137, v64, v65
	v_cvt_pk_bf16_f32 v138, v30, v31
	v_cvt_pk_bf16_f32 v139, v32, v33
	s_nop 0
	v_permlane32_swap_b32_e32 v136, v138
	v_permlane32_swap_b32_e32 v137, v139
	s_nop 0
	v_permlane16_swap_b32_e32 v136, v138
	v_permlane16_swap_b32_e32 v137, v139
	global_store_dwordx4 v132, v[136:139], s[8:9] nt
	s_nop 1
	v_cvt_pk_bf16_f32 v136, v58, v59
	v_cvt_pk_bf16_f32 v137, v60, v61
	v_cvt_pk_bf16_f32 v138, v26, v27
	v_cvt_pk_bf16_f32 v139, v28, v29
	s_nop 0
	v_permlane32_swap_b32_e32 v136, v138
	v_permlane32_swap_b32_e32 v137, v139
	s_nop 0
	v_permlane16_swap_b32_e32 v136, v138
	v_permlane16_swap_b32_e32 v137, v139
	v_add_u32_e32 v134, 0x15c00, v132
	global_store_dwordx4 v134, v[136:139], s[8:9] nt
	s_nop 1
	v_cvt_pk_bf16_f32 v136, v54, v55
	v_cvt_pk_bf16_f32 v137, v56, v57
	v_cvt_pk_bf16_f32 v138, v22, v23
	v_cvt_pk_bf16_f32 v139, v24, v25
	s_nop 0
	v_permlane32_swap_b32_e32 v136, v138
	v_permlane32_swap_b32_e32 v137, v139
	s_nop 0
	v_permlane16_swap_b32_e32 v136, v138
	v_permlane16_swap_b32_e32 v137, v139
	v_add_u32_e32 v134, 0x2b800, v132
	global_store_dwordx4 v134, v[136:139], s[8:9] nt
	s_nop 1
	v_cvt_pk_bf16_f32 v136, v50, v51
	v_cvt_pk_bf16_f32 v137, v52, v53
	v_cvt_pk_bf16_f32 v138, v18, v19
	v_cvt_pk_bf16_f32 v139, v20, v21
	s_nop 0
	v_permlane32_swap_b32_e32 v136, v138
	v_permlane32_swap_b32_e32 v137, v139
	s_nop 0
	v_permlane16_swap_b32_e32 v136, v138
	v_permlane16_swap_b32_e32 v137, v139
	v_add_u32_e32 v134, 0x41400, v132
	global_store_dwordx4 v134, v[136:139], s[8:9] nt
	s_nop 1
	v_cvt_pk_bf16_f32 v136, v46, v47
	v_cvt_pk_bf16_f32 v137, v48, v49
	v_cvt_pk_bf16_f32 v138, v14, v15
	v_cvt_pk_bf16_f32 v139, v16, v17
	s_nop 0
	v_permlane32_swap_b32_e32 v136, v138
	v_permlane32_swap_b32_e32 v137, v139
	s_nop 0
	v_permlane16_swap_b32_e32 v136, v138
	v_permlane16_swap_b32_e32 v137, v139
	v_add_u32_e32 v134, 0xae000, v132
	global_store_dwordx4 v134, v[136:139], s[8:9] nt
	s_nop 1
	v_cvt_pk_bf16_f32 v136, v42, v43
	v_cvt_pk_bf16_f32 v137, v44, v45
	v_cvt_pk_bf16_f32 v138, v10, v11
	v_cvt_pk_bf16_f32 v139, v12, v13
	s_nop 0
	v_permlane32_swap_b32_e32 v136, v138
	v_permlane32_swap_b32_e32 v137, v139
	s_nop 0
	v_permlane16_swap_b32_e32 v136, v138
	v_permlane16_swap_b32_e32 v137, v139
	v_add_u32_e32 v134, 0xc3c00, v132
	global_store_dwordx4 v134, v[136:139], s[8:9] nt
	s_nop 1
	v_cvt_pk_bf16_f32 v136, v38, v39
	v_cvt_pk_bf16_f32 v137, v40, v41
	v_cvt_pk_bf16_f32 v138, v6, v7
	v_cvt_pk_bf16_f32 v139, v8, v9
	s_nop 0
	v_permlane32_swap_b32_e32 v136, v138
	v_permlane32_swap_b32_e32 v137, v139
	s_nop 0
	v_permlane16_swap_b32_e32 v136, v138
	v_permlane16_swap_b32_e32 v137, v139
	v_add_u32_e32 v134, 0xd9800, v132
	global_store_dwordx4 v134, v[136:139], s[8:9] nt
	s_nop 1
	v_cvt_pk_bf16_f32 v136, v34, v35
	v_cvt_pk_bf16_f32 v137, v36, v37
	v_cvt_pk_bf16_f32 v138, v0, v1
	v_cvt_pk_bf16_f32 v139, v2, v3
	s_nop 0
	v_permlane32_swap_b32_e32 v136, v138
	v_permlane32_swap_b32_e32 v137, v139
	s_nop 0
	v_permlane16_swap_b32_e32 v136, v138
	v_permlane16_swap_b32_e32 v137, v139
	v_add_u32_e32 v134, 0xef400, v132
	global_store_dwordx4 v134, v[136:139], s[8:9] nt
	s_nop 1
	s_branch .Lipe1_done

; DI u16 f2bf(float x) { unsigned u = __float_as_uint(x); u += 0x7fffu + ((u >> 16) & 1u); return (u16)(u >> 16); }
; DI void phase_inproj(const Params& p, int layer, char* lds) {
;     ...
;         if (cw < DIN) {
;           float sc = 1.f;
;           if (col >= C_DQ && col < C_DK) sc = SC_DQ;
;           if (col >= C_SQ && col < C_SK) sc = SC_SQ;
;           const bool gate = col >= C_GATE;
; #pragma unroll
;           for (int ai = 0; ai < 2; ++ai)
; #pragma unroll
;             for (int m = 0; m < 4; ++m) {
; #pragma unroll
;               for (int j = 0; j < 4; ++j) {
;                 const int row = m0 + ai * 128 + wr8 * 64 + m * 16 + fq * 4 + j;
;                 float v = acc[ai][bj][m][n][j] * sc;
;                 if (gate) v = v * __builtin_amdgcn_rcpf(1.f + __expf(-v));
;                 dst[(size_t)row * dstr + fr] = f2bf(v);
;               }
.Lipe1_scaled:
	s_mul_i32 s10, s4, 0x15c0
	s_lshl_b32 s11, s25, 1
	s_add_u32 s10, s10, s11
	s_add_u32 s8, s50, s10
	s_addc_u32 s9, s51, 0
	v_mul_f32_e32 v62, v146, v62
	v_mul_f32_e32 v63, v146, v63
	v_mul_f32_e32 v64, v146, v64
	v_mul_f32_e32 v65, v146, v65
	v_mul_f32_e32 v30, v146, v30
	v_mul_f32_e32 v31, v146, v31
	v_mul_f32_e32 v32, v146, v32
	v_mul_f32_e32 v33, v146, v33
	v_cvt_pk_bf16_f32 v136, v62, v63
	v_cvt_pk_bf16_f32 v137, v64, v65
	v_cvt_pk_bf16_f32 v138, v30, v31
	v_cvt_pk_bf16_f32 v139, v32, v33
	s_nop 0
	v_permlane32_swap_b32_e32 v136, v138
	v_permlane32_swap_b32_e32 v137, v139
	s_nop 0
	v_permlane16_swap_b32_e32 v136, v138
	v_permlane16_swap_b32_e32 v137, v139
	global_store_dwordx4 v132, v[136:139], s[8:9] nt
	s_nop 1
	v_mul_f32_e32 v58, v146, v58
	v_mul_f32_e32 v59, v146, v59
	v_mul_f32_e32 v60, v146, v60
	v_mul_f32_e32 v61, v146, v61
	v_mul_f32_e32 v26, v146, v26
	v_mul_f32_e32 v27, v146, v27
	v_mul_f32_e32 v28, v146, v28
	v_mul_f32_e32 v29, v146, v29
	v_cvt_pk_bf16_f32 v136, v58, v59
	v_cvt_pk_bf16_f32 v137, v60, v61
	v_cvt_pk_bf16_f32 v138, v26, v27
	v_cvt_pk_bf16_f32 v139, v28, v29
	s_nop 0
	v_permlane32_swap_b32_e32 v136, v138
	v_permlane32_swap_b32_e32 v137, v139
	s_nop 0
	v_permlane16_swap_b32_e32 v136, v138
	v_permlane16_swap_b32_e32 v137, v139
	v_add_u32_e32 v134, 0x15c00, v132
	global_store_dwordx4 v134, v[136:139], s[8:9] nt
	s_nop 1
	v_mul_f32_e32 v54, v146, v54
	v_mul_f32_e32 v55, v146, v55
	v_mul_f32_e32 v56, v146, v56
	v_mul_f32_e32 v57, v146, v57
	v_mul_f32_e32 v22, v146, v22
	v_mul_f32_e32 v23, v146, v23
	v_mul_f32_e32 v24, v146, v24
	v_mul_f32_e32 v25, v146, v25
	v_cvt_pk_bf16_f32 v136, v54, v55
	v_cvt_pk_bf16_f32 v137, v56, v57
	v_cvt_pk_bf16_f32 v138, v22, v23
	v_cvt_pk_bf16_f32 v139, v24, v25
	s_nop 0
	v_permlane32_swap_b32_e32 v136, v138
	v_permlane32_swap_b32_e32 v137, v139
	s_nop 0
	v_permlane16_swap_b32_e32 v136, v138
	v_permlane16_swap_b32_e32 v137, v139
	v_add_u32_e32 v134, 0x2b800, v132
	global_store_dwordx4 v134, v[136:139], s[8:9] nt
	s_nop 1
	v_mul_f32_e32 v50, v146, v50
	v_mul_f32_e32 v51, v146, v51
	v_mul_f32_e32 v52, v146, v52
	v_mul_f32_e32 v53, v146, v53
	v_mul_f32_e32 v18, v146, v18
	v_mul_f32_e32 v19, v146, v19
	v_mul_f32_e32 v20, v146, v20
	v_mul_f32_e32 v21, v146, v21
	v_cvt_pk_bf16_f32 v136, v50, v51
	v_cvt_pk_bf16_f32 v137, v52, v53
	v_cvt_pk_bf16_f32 v138, v18, v19
	v_cvt_pk_bf16_f32 v139, v20, v21
	s_nop 0
	v_permlane32_swap_b32_e32 v136, v138
	v_permlane32_swap_b32_e32 v137, v139
	s_nop 0
	v_permlane16_swap_b32_e32 v136, v138
	v_permlane16_swap_b32_e32 v137, v139
	v_add_u32_e32 v134, 0x41400, v132
	global_store_dwordx4 v134, v[136:139], s[8:9] nt
	s_nop 1
	v_mul_f32_e32 v46, v146, v46
	v_mul_f32_e32 v47, v146, v47
	v_mul_f32_e32 v48, v146, v48
	v_mul_f32_e32 v49, v146, v49
	v_mul_f32_e32 v14, v146, v14
	v_mul_f32_e32 v15, v146, v15
	v_mul_f32_e32 v16, v146, v16
	v_mul_f32_e32 v17, v146, v17
	v_cvt_pk_bf16_f32 v136, v46, v47
	v_cvt_pk_bf16_f32 v137, v48, v49
	v_cvt_pk_bf16_f32 v138, v14, v15
	v_cvt_pk_bf16_f32 v139, v16, v17
	s_nop 0
	v_permlane32_swap_b32_e32 v136, v138
	v_permlane32_swap_b32_e32 v137, v139
	s_nop 0
	v_permlane16_swap_b32_e32 v136, v138
	v_permlane16_swap_b32_e32 v137, v139
	v_add_u32_e32 v134, 0xae000, v132
	global_store_dwordx4 v134, v[136:139], s[8:9] nt
	s_nop 1
	v_mul_f32_e32 v42, v146, v42
	v_mul_f32_e32 v43, v146, v43
	v_mul_f32_e32 v44, v146, v44
	v_mul_f32_e32 v45, v146, v45
	v_mul_f32_e32 v10, v146, v10
	v_mul_f32_e32 v11, v146, v11
	v_mul_f32_e32 v12, v146, v12
	v_mul_f32_e32 v13, v146, v13
	v_cvt_pk_bf16_f32 v136, v42, v43
	v_cvt_pk_bf16_f32 v137, v44, v45
	v_cvt_pk_bf16_f32 v138, v10, v11
	v_cvt_pk_bf16_f32 v139, v12, v13
	s_nop 0
	v_permlane32_swap_b32_e32 v136, v138
	v_permlane32_swap_b32_e32 v137, v139
	s_nop 0
	v_permlane16_swap_b32_e32 v136, v138
	v_permlane16_swap_b32_e32 v137, v139
	v_add_u32_e32 v134, 0xc3c00, v132
	global_store_dwordx4 v134, v[136:139], s[8:9] nt
	s_nop 1
	v_mul_f32_e32 v38, v146, v38
	v_mul_f32_e32 v39, v146, v39
	v_mul_f32_e32 v40, v146, v40
	v_mul_f32_e32 v41, v146, v41
	v_mul_f32_e32 v6, v146, v6
	v_mul_f32_e32 v7, v146, v7
	v_mul_f32_e32 v8, v146, v8
	v_mul_f32_e32 v9, v146, v9
	v_cvt_pk_bf16_f32 v136, v38, v39
	v_cvt_pk_bf16_f32 v137, v40, v41
	v_cvt_pk_bf16_f32 v138, v6, v7
	v_cvt_pk_bf16_f32 v139, v8, v9
	s_nop 0
	v_permlane32_swap_b32_e32 v136, v138
	v_permlane32_swap_b32_e32 v137, v139
	s_nop 0
	v_permlane16_swap_b32_e32 v136, v138
	v_permlane16_swap_b32_e32 v137, v139
	v_add_u32_e32 v134, 0xd9800, v132
	global_store_dwordx4 v134, v[136:139], s[8:9] nt
	s_nop 1
	v_mul_f32_e32 v34, v146, v34
	v_mul_f32_e32 v35, v146, v35
	v_mul_f32_e32 v36, v146, v36
	v_mul_f32_e32 v37, v146, v37
	v_mul_f32_e32 v0, v146, v0
	v_mul_f32_e32 v1, v146, v1
	v_mul_f32_e32 v2, v146, v2
	v_mul_f32_e32 v3, v146, v3
	v_cvt_pk_bf16_f32 v136, v34, v35
	v_cvt_pk_bf16_f32 v137, v36, v37
	v_cvt_pk_bf16_f32 v138, v0, v1
	v_cvt_pk_bf16_f32 v139, v2, v3
	s_nop 0
	v_permlane32_swap_b32_e32 v136, v138
	v_permlane32_swap_b32_e32 v137, v139
	s_nop 0
	v_permlane16_swap_b32_e32 v136, v138
	v_permlane16_swap_b32_e32 v137, v139
	v_add_u32_e32 v134, 0xef400, v132
	global_store_dwordx4 v134, v[136:139], s[8:9] nt
	s_nop 1
	s_branch .Lipe1_done
; DI u16 f2bf(float x) { unsigned u = __float_as_uint(x); u += 0x7fffu + ((u >> 16) & 1u); return (u16)(u >> 16); }
; DI void phase_inproj(const Params& p, int layer, char* lds) {
;     ...
;           const bool gate = col >= C_GATE;
; #pragma unroll
;           for (int ai = 0; ai < 2; ++ai)
; #pragma unroll
;             for (int m = 0; m < 4; ++m) {
; #pragma unroll
;               for (int j = 0; j < 4; ++j) {
;                 const int row = m0 + ai * 128 + wr8 * 64 + m * 16 + fq * 4 + j;
;                 float v = acc[ai][bj][m][n][j] * sc;
;                 if (gate) v = v * __builtin_amdgcn_rcpf(1.f + __expf(-v));
;                 dst[(size_t)row * dstr + fr] = f2bf(v);
.Lipe1_gate:
	s_mul_i32 s10, s4, 0x15c0
	s_lshl_b32 s11, s25, 1
	s_add_u32 s10, s10, s11
	s_add_u32 s8, s50, s10
	s_addc_u32 s9, s51, 0
	v_mul_f32_e32 v140, 0xbfb8aa3b, v62
	v_mul_f32_e32 v141, 0xbfb8aa3b, v63
	v_mul_f32_e32 v142, 0xbfb8aa3b, v64
	v_mul_f32_e32 v143, 0xbfb8aa3b, v65
	v_exp_f32_e32 v140, v140
	v_exp_f32_e32 v141, v141
	v_exp_f32_e32 v142, v142
	v_exp_f32_e32 v143, v143
	v_add_f32_e32 v140, 1.0, v140
	v_add_f32_e32 v141, 1.0, v141
	v_add_f32_e32 v142, 1.0, v142
	v_add_f32_e32 v143, 1.0, v143
	v_rcp_f32_e32 v140, v140
	v_rcp_f32_e32 v141, v141
	v_rcp_f32_e32 v142, v142
	v_rcp_f32_e32 v143, v143
	v_mul_f32_e32 v62, v62, v140
	v_mul_f32_e32 v63, v63, v141
	v_mul_f32_e32 v64, v64, v142
	v_mul_f32_e32 v65, v65, v143
	v_mul_f32_e32 v140, 0xbfb8aa3b, v30
	v_mul_f32_e32 v141, 0xbfb8aa3b, v31
	v_mul_f32_e32 v142, 0xbfb8aa3b, v32
	v_mul_f32_e32 v143, 0xbfb8aa3b, v33
	v_exp_f32_e32 v140, v140
	v_exp_f32_e32 v141, v141
	v_exp_f32_e32 v142, v142
	v_exp_f32_e32 v143, v143
	v_add_f32_e32 v140, 1.0, v140
	v_add_f32_e32 v141, 1.0, v141
	v_add_f32_e32 v142, 1.0, v142
	v_add_f32_e32 v143, 1.0, v143
	v_rcp_f32_e32 v140, v140
	v_rcp_f32_e32 v141, v141
	v_rcp_f32_e32 v142, v142
	v_rcp_f32_e32 v143, v143
	v_mul_f32_e32 v30, v30, v140
	v_mul_f32_e32 v31, v31, v141
	v_mul_f32_e32 v32, v32, v142
	v_mul_f32_e32 v33, v33, v143
	v_cvt_pk_bf16_f32 v136, v62, v63
	v_cvt_pk_bf16_f32 v137, v64, v65
	v_cvt_pk_bf16_f32 v138, v30, v31
	v_cvt_pk_bf16_f32 v139, v32, v33
	s_nop 0
	v_permlane32_swap_b32_e32 v136, v138
	v_permlane32_swap_b32_e32 v137, v139
	s_nop 0
	v_permlane16_swap_b32_e32 v136, v138
	v_permlane16_swap_b32_e32 v137, v139
	global_store_dwordx4 v132, v[136:139], s[8:9] nt
	s_nop 1
	v_mul_f32_e32 v140, 0xbfb8aa3b, v58
	v_mul_f32_e32 v141, 0xbfb8aa3b, v59
	v_mul_f32_e32 v142, 0xbfb8aa3b, v60
	v_mul_f32_e32 v143, 0xbfb8aa3b, v61
	v_exp_f32_e32 v140, v140
	v_exp_f32_e32 v141, v141
	v_exp_f32_e32 v142, v142
	v_exp_f32_e32 v143, v143
	v_add_f32_e32 v140, 1.0, v140
	v_add_f32_e32 v141, 1.0, v141
	v_add_f32_e32 v142, 1.0, v142
	v_add_f32_e32 v143, 1.0, v143
	v_rcp_f32_e32 v140, v140
	v_rcp_f32_e32 v141, v141
	v_rcp_f32_e32 v142, v142
	v_rcp_f32_e32 v143, v143
	v_mul_f32_e32 v58, v58, v140
	v_mul_f32_e32 v59, v59, v141
	v_mul_f32_e32 v60, v60, v142
	v_mul_f32_e32 v61, v61, v143
	v_mul_f32_e32 v140, 0xbfb8aa3b, v26
	v_mul_f32_e32 v141, 0xbfb8aa3b, v27
	v_mul_f32_e32 v142, 0xbfb8aa3b, v28
	v_mul_f32_e32 v143, 0xbfb8aa3b, v29
	v_exp_f32_e32 v140, v140
	v_exp_f32_e32 v141, v141
	v_exp_f32_e32 v142, v142
	v_exp_f32_e32 v143, v143
	v_add_f32_e32 v140, 1.0, v140
	v_add_f32_e32 v141, 1.0, v141
	v_add_f32_e32 v142, 1.0, v142
	v_add_f32_e32 v143, 1.0, v143
	v_rcp_f32_e32 v140, v140
	v_rcp_f32_e32 v141, v141
	v_rcp_f32_e32 v142, v142
	v_rcp_f32_e32 v143, v143
	v_mul_f32_e32 v26, v26, v140
	v_mul_f32_e32 v27, v27, v141
	v_mul_f32_e32 v28, v28, v142
	v_mul_f32_e32 v29, v29, v143
	v_cvt_pk_bf16_f32 v136, v58, v59
	v_cvt_pk_bf16_f32 v137, v60, v61
	v_cvt_pk_bf16_f32 v138, v26, v27
	v_cvt_pk_bf16_f32 v139, v28, v29
	s_nop 0
	v_permlane32_swap_b32_e32 v136, v138
	v_permlane32_swap_b32_e32 v137, v139
	s_nop 0
	v_permlane16_swap_b32_e32 v136, v138
	v_permlane16_swap_b32_e32 v137, v139
	v_add_u32_e32 v134, 0x15c00, v132
	global_store_dwordx4 v134, v[136:139], s[8:9] nt
	s_nop 1
	v_mul_f32_e32 v140, 0xbfb8aa3b, v54
	v_mul_f32_e32 v141, 0xbfb8aa3b, v55
	v_mul_f32_e32 v142, 0xbfb8aa3b, v56
	v_mul_f32_e32 v143, 0xbfb8aa3b, v57
	v_exp_f32_e32 v140, v140
	v_exp_f32_e32 v141, v141
	v_exp_f32_e32 v142, v142
	v_exp_f32_e32 v143, v143
	v_add_f32_e32 v140, 1.0, v140
	v_add_f32_e32 v141, 1.0, v141
	v_add_f32_e32 v142, 1.0, v142
	v_add_f32_e32 v143, 1.0, v143
	v_rcp_f32_e32 v140, v140
	v_rcp_f32_e32 v141, v141
	v_rcp_f32_e32 v142, v142
	v_rcp_f32_e32 v143, v143
	v_mul_f32_e32 v54, v54, v140
	v_mul_f32_e32 v55, v55, v141
	v_mul_f32_e32 v56, v56, v142
	v_mul_f32_e32 v57, v57, v143
	v_mul_f32_e32 v140, 0xbfb8aa3b, v22
	v_mul_f32_e32 v141, 0xbfb8aa3b, v23
	v_mul_f32_e32 v142, 0xbfb8aa3b, v24
	v_mul_f32_e32 v143, 0xbfb8aa3b, v25
	v_exp_f32_e32 v140, v140
	v_exp_f32_e32 v141, v141
	v_exp_f32_e32 v142, v142
	v_exp_f32_e32 v143, v143
	v_add_f32_e32 v140, 1.0, v140
	v_add_f32_e32 v141, 1.0, v141
	v_add_f32_e32 v142, 1.0, v142
	v_add_f32_e32 v143, 1.0, v143
	v_rcp_f32_e32 v140, v140
	v_rcp_f32_e32 v141, v141
	v_rcp_f32_e32 v142, v142
	v_rcp_f32_e32 v143, v143
	v_mul_f32_e32 v22, v22, v140
	v_mul_f32_e32 v23, v23, v141
	v_mul_f32_e32 v24, v24, v142
	v_mul_f32_e32 v25, v25, v143
	v_cvt_pk_bf16_f32 v136, v54, v55
	v_cvt_pk_bf16_f32 v137, v56, v57
	v_cvt_pk_bf16_f32 v138, v22, v23
	v_cvt_pk_bf16_f32 v139, v24, v25
	s_nop 0
	v_permlane32_swap_b32_e32 v136, v138
	v_permlane32_swap_b32_e32 v137, v139
	s_nop 0
	v_permlane16_swap_b32_e32 v136, v138
	v_permlane16_swap_b32_e32 v137, v139
	v_add_u32_e32 v134, 0x2b800, v132
	global_store_dwordx4 v134, v[136:139], s[8:9] nt
	s_nop 1
	v_mul_f32_e32 v140, 0xbfb8aa3b, v50
	v_mul_f32_e32 v141, 0xbfb8aa3b, v51
	v_mul_f32_e32 v142, 0xbfb8aa3b, v52
	v_mul_f32_e32 v143, 0xbfb8aa3b, v53
	v_exp_f32_e32 v140, v140
	v_exp_f32_e32 v141, v141
	v_exp_f32_e32 v142, v142
	v_exp_f32_e32 v143, v143
	v_add_f32_e32 v140, 1.0, v140
	v_add_f32_e32 v141, 1.0, v141
	v_add_f32_e32 v142, 1.0, v142
	v_add_f32_e32 v143, 1.0, v143
	v_rcp_f32_e32 v140, v140
	v_rcp_f32_e32 v141, v141
	v_rcp_f32_e32 v142, v142
	v_rcp_f32_e32 v143, v143
	v_mul_f32_e32 v50, v50, v140
	v_mul_f32_e32 v51, v51, v141
	v_mul_f32_e32 v52, v52, v142
	v_mul_f32_e32 v53, v53, v143
	v_mul_f32_e32 v140, 0xbfb8aa3b, v18
	v_mul_f32_e32 v141, 0xbfb8aa3b, v19
	v_mul_f32_e32 v142, 0xbfb8aa3b, v20
	v_mul_f32_e32 v143, 0xbfb8aa3b, v21
; DI u16 f2bf(float x) { unsigned u = __float_as_uint(x); u += 0x7fffu + ((u >> 16) & 1u); return (u16)(u >> 16); }
; DI void phase_inproj(const Params& p, int layer, char* lds) {
;     ...
;           const bool gate = col >= C_GATE;
; #pragma unroll
;           for (int ai = 0; ai < 2; ++ai)
; #pragma unroll
;             for (int m = 0; m < 4; ++m) {
; #pragma unroll
;               for (int j = 0; j < 4; ++j) {
;                 const int row = m0 + ai * 128 + wr8 * 64 + m * 16 + fq * 4 + j;
;                 float v = acc[ai][bj][m][n][j] * sc;
;                 if (gate) v = v * __builtin_amdgcn_rcpf(1.f + __expf(-v));
;                 dst[(size_t)row * dstr + fr] = f2bf(v);
	v_exp_f32_e32 v140, v140
	v_exp_f32_e32 v141, v141
	v_exp_f32_e32 v142, v142
	v_exp_f32_e32 v143, v143
	v_add_f32_e32 v140, 1.0, v140
	v_add_f32_e32 v141, 1.0, v141
	v_add_f32_e32 v142, 1.0, v142
	v_add_f32_e32 v143, 1.0, v143
	v_rcp_f32_e32 v140, v140
	v_rcp_f32_e32 v141, v141
	v_rcp_f32_e32 v142, v142
	v_rcp_f32_e32 v143, v143
	v_mul_f32_e32 v18, v18, v140
	v_mul_f32_e32 v19, v19, v141
	v_mul_f32_e32 v20, v20, v142
	v_mul_f32_e32 v21, v21, v143
	v_cvt_pk_bf16_f32 v136, v50, v51
	v_cvt_pk_bf16_f32 v137, v52, v53
	v_cvt_pk_bf16_f32 v138, v18, v19
	v_cvt_pk_bf16_f32 v139, v20, v21
	s_nop 0
	v_permlane32_swap_b32_e32 v136, v138
	v_permlane32_swap_b32_e32 v137, v139
	s_nop 0
	v_permlane16_swap_b32_e32 v136, v138
	v_permlane16_swap_b32_e32 v137, v139
	v_add_u32_e32 v134, 0x41400, v132
	global_store_dwordx4 v134, v[136:139], s[8:9] nt
	s_nop 1
	v_mul_f32_e32 v140, 0xbfb8aa3b, v46
	v_mul_f32_e32 v141, 0xbfb8aa3b, v47
	v_mul_f32_e32 v142, 0xbfb8aa3b, v48
	v_mul_f32_e32 v143, 0xbfb8aa3b, v49
	v_exp_f32_e32 v140, v140
	v_exp_f32_e32 v141, v141
	v_exp_f32_e32 v142, v142
	v_exp_f32_e32 v143, v143
	v_add_f32_e32 v140, 1.0, v140
	v_add_f32_e32 v141, 1.0, v141
	v_add_f32_e32 v142, 1.0, v142
	v_add_f32_e32 v143, 1.0, v143
	v_rcp_f32_e32 v140, v140
	v_rcp_f32_e32 v141, v141
	v_rcp_f32_e32 v142, v142
	v_rcp_f32_e32 v143, v143
	v_mul_f32_e32 v46, v46, v140
	v_mul_f32_e32 v47, v47, v141
	v_mul_f32_e32 v48, v48, v142
	v_mul_f32_e32 v49, v49, v143
	v_mul_f32_e32 v140, 0xbfb8aa3b, v14
	v_mul_f32_e32 v141, 0xbfb8aa3b, v15
	v_mul_f32_e32 v142, 0xbfb8aa3b, v16
	v_mul_f32_e32 v143, 0xbfb8aa3b, v17
	v_exp_f32_e32 v140, v140
	v_exp_f32_e32 v141, v141
	v_exp_f32_e32 v142, v142
	v_exp_f32_e32 v143, v143
	v_add_f32_e32 v140, 1.0, v140
	v_add_f32_e32 v141, 1.0, v141
	v_add_f32_e32 v142, 1.0, v142
	v_add_f32_e32 v143, 1.0, v143
	v_rcp_f32_e32 v140, v140
	v_rcp_f32_e32 v141, v141
	v_rcp_f32_e32 v142, v142
	v_rcp_f32_e32 v143, v143
	v_mul_f32_e32 v14, v14, v140
	v_mul_f32_e32 v15, v15, v141
	v_mul_f32_e32 v16, v16, v142
	v_mul_f32_e32 v17, v17, v143
	v_cvt_pk_bf16_f32 v136, v46, v47
	v_cvt_pk_bf16_f32 v137, v48, v49
	v_cvt_pk_bf16_f32 v138, v14, v15
	v_cvt_pk_bf16_f32 v139, v16, v17
	s_nop 0
	v_permlane32_swap_b32_e32 v136, v138
	v_permlane32_swap_b32_e32 v137, v139
	s_nop 0
	v_permlane16_swap_b32_e32 v136, v138
	v_permlane16_swap_b32_e32 v137, v139
	v_add_u32_e32 v134, 0xae000, v132
	global_store_dwordx4 v134, v[136:139], s[8:9] nt
	s_nop 1
	v_mul_f32_e32 v140, 0xbfb8aa3b, v42
	v_mul_f32_e32 v141, 0xbfb8aa3b, v43
	v_mul_f32_e32 v142, 0xbfb8aa3b, v44
	v_mul_f32_e32 v143, 0xbfb8aa3b, v45
	v_exp_f32_e32 v140, v140
	v_exp_f32_e32 v141, v141
	v_exp_f32_e32 v142, v142
	v_exp_f32_e32 v143, v143
	v_add_f32_e32 v140, 1.0, v140
	v_add_f32_e32 v141, 1.0, v141
	v_add_f32_e32 v142, 1.0, v142
	v_add_f32_e32 v143, 1.0, v143
	v_rcp_f32_e32 v140, v140
	v_rcp_f32_e32 v141, v141
	v_rcp_f32_e32 v142, v142
	v_rcp_f32_e32 v143, v143
	v_mul_f32_e32 v42, v42, v140
	v_mul_f32_e32 v43, v43, v141
	v_mul_f32_e32 v44, v44, v142
	v_mul_f32_e32 v45, v45, v143
	v_mul_f32_e32 v140, 0xbfb8aa3b, v10
	v_mul_f32_e32 v141, 0xbfb8aa3b, v11
	v_mul_f32_e32 v142, 0xbfb8aa3b, v12
	v_mul_f32_e32 v143, 0xbfb8aa3b, v13
	v_exp_f32_e32 v140, v140
	v_exp_f32_e32 v141, v141
	v_exp_f32_e32 v142, v142
	v_exp_f32_e32 v143, v143
	v_add_f32_e32 v140, 1.0, v140
	v_add_f32_e32 v141, 1.0, v141
	v_add_f32_e32 v142, 1.0, v142
	v_add_f32_e32 v143, 1.0, v143
	v_rcp_f32_e32 v140, v140
	v_rcp_f32_e32 v141, v141
	v_rcp_f32_e32 v142, v142
	v_rcp_f32_e32 v143, v143
	v_mul_f32_e32 v10, v10, v140
	v_mul_f32_e32 v11, v11, v141
	v_mul_f32_e32 v12, v12, v142
; DI u16 f2bf(float x) { unsigned u = __float_as_uint(x); u += 0x7fffu + ((u >> 16) & 1u); return (u16)(u >> 16); }
; DI void phase_inproj(const Params& p, int layer, char* lds) {
;     ...
;           const bool gate = col >= C_GATE;
; #pragma unroll
;           for (int ai = 0; ai < 2; ++ai)
; #pragma unroll
;             for (int m = 0; m < 4; ++m) {
; #pragma unroll
;               for (int j = 0; j < 4; ++j) {
;                 const int row = m0 + ai * 128 + wr8 * 64 + m * 16 + fq * 4 + j;
;                 float v = acc[ai][bj][m][n][j] * sc;
;                 if (gate) v = v * __builtin_amdgcn_rcpf(1.f + __expf(-v));
;                 dst[(size_t)row * dstr + fr] = f2bf(v);
	v_mul_f32_e32 v13, v13, v143
	v_cvt_pk_bf16_f32 v136, v42, v43
	v_cvt_pk_bf16_f32 v137, v44, v45
	v_cvt_pk_bf16_f32 v138, v10, v11
	v_cvt_pk_bf16_f32 v139, v12, v13
	s_nop 0
	v_permlane32_swap_b32_e32 v136, v138
	v_permlane32_swap_b32_e32 v137, v139
	s_nop 0
	v_permlane16_swap_b32_e32 v136, v138
	v_permlane16_swap_b32_e32 v137, v139
	v_add_u32_e32 v134, 0xc3c00, v132
	global_store_dwordx4 v134, v[136:139], s[8:9] nt
	s_nop 1
	v_mul_f32_e32 v140, 0xbfb8aa3b, v38
	v_mul_f32_e32 v141, 0xbfb8aa3b, v39
	v_mul_f32_e32 v142, 0xbfb8aa3b, v40
	v_mul_f32_e32 v143, 0xbfb8aa3b, v41
	v_exp_f32_e32 v140, v140
	v_exp_f32_e32 v141, v141
	v_exp_f32_e32 v142, v142
	v_exp_f32_e32 v143, v143
	v_add_f32_e32 v140, 1.0, v140
	v_add_f32_e32 v141, 1.0, v141
	v_add_f32_e32 v142, 1.0, v142
	v_add_f32_e32 v143, 1.0, v143
	v_rcp_f32_e32 v140, v140
	v_rcp_f32_e32 v141, v141
	v_rcp_f32_e32 v142, v142
	v_rcp_f32_e32 v143, v143
	v_mul_f32_e32 v38, v38, v140
	v_mul_f32_e32 v39, v39, v141
	v_mul_f32_e32 v40, v40, v142
	v_mul_f32_e32 v41, v41, v143
	v_mul_f32_e32 v140, 0xbfb8aa3b, v6
	v_mul_f32_e32 v141, 0xbfb8aa3b, v7
	v_mul_f32_e32 v142, 0xbfb8aa3b, v8
	v_mul_f32_e32 v143, 0xbfb8aa3b, v9
	v_exp_f32_e32 v140, v140
	v_exp_f32_e32 v141, v141
	v_exp_f32_e32 v142, v142
	v_exp_f32_e32 v143, v143
	v_add_f32_e32 v140, 1.0, v140
	v_add_f32_e32 v141, 1.0, v141
	v_add_f32_e32 v142, 1.0, v142
	v_add_f32_e32 v143, 1.0, v143
	v_rcp_f32_e32 v140, v140
	v_rcp_f32_e32 v141, v141
	v_rcp_f32_e32 v142, v142
	v_rcp_f32_e32 v143, v143
	v_mul_f32_e32 v6, v6, v140
	v_mul_f32_e32 v7, v7, v141
	v_mul_f32_e32 v8, v8, v142
	v_mul_f32_e32 v9, v9, v143
	v_cvt_pk_bf16_f32 v136, v38, v39
	v_cvt_pk_bf16_f32 v137, v40, v41
	v_cvt_pk_bf16_f32 v138, v6, v7
	v_cvt_pk_bf16_f32 v139, v8, v9
	s_nop 0
	v_permlane32_swap_b32_e32 v136, v138
	v_permlane32_swap_b32_e32 v137, v139
	s_nop 0
	v_permlane16_swap_b32_e32 v136, v138
	v_permlane16_swap_b32_e32 v137, v139
	v_add_u32_e32 v134, 0xd9800, v132
	global_store_dwordx4 v134, v[136:139], s[8:9] nt
	s_nop 1
	v_mul_f32_e32 v140, 0xbfb8aa3b, v34
	v_mul_f32_e32 v141, 0xbfb8aa3b, v35
	v_mul_f32_e32 v142, 0xbfb8aa3b, v36
	v_mul_f32_e32 v143, 0xbfb8aa3b, v37
	v_exp_f32_e32 v140, v140
	v_exp_f32_e32 v141, v141
	v_exp_f32_e32 v142, v142
	v_exp_f32_e32 v143, v143
	v_add_f32_e32 v140, 1.0, v140
	v_add_f32_e32 v141, 1.0, v141
	v_add_f32_e32 v142, 1.0, v142
	v_add_f32_e32 v143, 1.0, v143
	v_rcp_f32_e32 v140, v140
	v_rcp_f32_e32 v141, v141
	v_rcp_f32_e32 v142, v142
	v_rcp_f32_e32 v143, v143
	v_mul_f32_e32 v34, v34, v140
	v_mul_f32_e32 v35, v35, v141
	v_mul_f32_e32 v36, v36, v142
	v_mul_f32_e32 v37, v37, v143
	v_mul_f32_e32 v140, 0xbfb8aa3b, v0
	v_mul_f32_e32 v141, 0xbfb8aa3b, v1
	v_mul_f32_e32 v142, 0xbfb8aa3b, v2
	v_mul_f32_e32 v143, 0xbfb8aa3b, v3
	v_exp_f32_e32 v140, v140
	v_exp_f32_e32 v141, v141
	v_exp_f32_e32 v142, v142
	v_exp_f32_e32 v143, v143
	v_add_f32_e32 v140, 1.0, v140
	v_add_f32_e32 v141, 1.0, v141
	v_add_f32_e32 v142, 1.0, v142
	v_add_f32_e32 v143, 1.0, v143
	v_rcp_f32_e32 v140, v140
	v_rcp_f32_e32 v141, v141
	v_rcp_f32_e32 v142, v142
	v_rcp_f32_e32 v143, v143
	v_mul_f32_e32 v0, v0, v140
	v_mul_f32_e32 v1, v1, v141
	v_mul_f32_e32 v2, v2, v142
	v_mul_f32_e32 v3, v3, v143
	v_cvt_pk_bf16_f32 v136, v34, v35
	v_cvt_pk_bf16_f32 v137, v36, v37
	v_cvt_pk_bf16_f32 v138, v0, v1
	v_cvt_pk_bf16_f32 v139, v2, v3
	s_nop 0
	v_permlane32_swap_b32_e32 v136, v138
	v_permlane32_swap_b32_e32 v137, v139
	s_nop 0
	v_permlane16_swap_b32_e32 v136, v138
	v_permlane16_swap_b32_e32 v137, v139
	v_add_u32_e32 v134, 0xef400, v132
	global_store_dwordx4 v134, v[136:139], s[8:9] nt
	s_nop 1
	s_branch .Lipe1_done

; DI void phase_inproj(const Params& p, int layer, char* lds) {
;     ...
;           if (cw >= C_DK && cw < C_DV) { const int o = cw - C_DK; dst = (u16*)(p.ws + OFF_DK) + ((size_t)(bb * 3 * S + (o >> 6) * S) << 6) + (o & 63); dstr = 64; }
;           else if (cw >= C_DV && cw < C_SQ) { const int o = cw - C_DV; dst = (u16*)(p.ws + OFF_DV) + ((size_t)(bb * 3 * S + (o >> 6) * S) << 6) + (o & 63); dstr = 64; }
;           else if (cw >= C_SK && cw < C_SV) { const int o = cw - C_SK; dst = (u16*)(p.ws + OFF_SK) + ((size_t)(bb * 1 * S + (o >> 6) * S) << 6) + (o & 63); dstr = 64; }
;           else if (cw >= C_SV && cw < C_GATE) { const int o = cw - C_SV; dst = (u16*)(p.ws + OFF_SV) + ((size_t)(bb * 1 * S + (o >> 6) * S) << 6) + (o & 63); dstr = 64; }
.Lipe1_kv:
	v_cvt_pk_bf16_f32 v136, v62, v63
	v_cvt_pk_bf16_f32 v137, v64, v65
	v_cvt_pk_bf16_f32 v138, v30, v31
	v_cvt_pk_bf16_f32 v139, v32, v33
	s_nop 0
	v_permlane32_swap_b32_e32 v136, v138
	v_permlane32_swap_b32_e32 v137, v139
	s_nop 0
	v_permlane16_swap_b32_e32 v136, v138
	v_permlane16_swap_b32_e32 v137, v139
	global_store_dwordx4 v133, v[136:139], s[8:9] nt
	s_nop 1
	v_cvt_pk_bf16_f32 v136, v58, v59
	v_cvt_pk_bf16_f32 v137, v60, v61
	v_cvt_pk_bf16_f32 v138, v26, v27
	v_cvt_pk_bf16_f32 v139, v28, v29
	s_nop 0
	v_permlane32_swap_b32_e32 v136, v138
	v_permlane32_swap_b32_e32 v137, v139
	s_nop 0
	v_permlane16_swap_b32_e32 v136, v138
	v_permlane16_swap_b32_e32 v137, v139
	v_add_u32_e32 v134, 0x800, v133
	global_store_dwordx4 v134, v[136:139], s[8:9] nt
	s_nop 1
	v_cvt_pk_bf16_f32 v136, v54, v55
	v_cvt_pk_bf16_f32 v137, v56, v57
	v_cvt_pk_bf16_f32 v138, v22, v23
	v_cvt_pk_bf16_f32 v139, v24, v25
	s_nop 0
	v_permlane32_swap_b32_e32 v136, v138
	v_permlane32_swap_b32_e32 v137, v139
	s_nop 0
	v_permlane16_swap_b32_e32 v136, v138
	v_permlane16_swap_b32_e32 v137, v139
	v_add_u32_e32 v134, 0x1000, v133
	global_store_dwordx4 v134, v[136:139], s[8:9] nt
	s_nop 1
	v_cvt_pk_bf16_f32 v136, v50, v51
	v_cvt_pk_bf16_f32 v137, v52, v53
	v_cvt_pk_bf16_f32 v138, v18, v19
	v_cvt_pk_bf16_f32 v139, v20, v21
	s_nop 0
	v_permlane32_swap_b32_e32 v136, v138
	v_permlane32_swap_b32_e32 v137, v139
	s_nop 0
	v_permlane16_swap_b32_e32 v136, v138
	v_permlane16_swap_b32_e32 v137, v139
	v_add_u32_e32 v134, 0x1800, v133
	global_store_dwordx4 v134, v[136:139], s[8:9] nt
	s_nop 1
	v_cvt_pk_bf16_f32 v136, v46, v47
	v_cvt_pk_bf16_f32 v137, v48, v49
	v_cvt_pk_bf16_f32 v138, v14, v15
	v_cvt_pk_bf16_f32 v139, v16, v17
	s_nop 0
	v_permlane32_swap_b32_e32 v136, v138
	v_permlane32_swap_b32_e32 v137, v139
	s_nop 0
	v_permlane16_swap_b32_e32 v136, v138
	v_permlane16_swap_b32_e32 v137, v139
	v_add_u32_e32 v134, 0x4000, v133
	global_store_dwordx4 v134, v[136:139], s[8:9] nt
	s_nop 1
	v_cvt_pk_bf16_f32 v136, v42, v43
	v_cvt_pk_bf16_f32 v137, v44, v45
	v_cvt_pk_bf16_f32 v138, v10, v11
	v_cvt_pk_bf16_f32 v139, v12, v13
	s_nop 0
	v_permlane32_swap_b32_e32 v136, v138
	v_permlane32_swap_b32_e32 v137, v139
	s_nop 0
	v_permlane16_swap_b32_e32 v136, v138
	v_permlane16_swap_b32_e32 v137, v139
	v_add_u32_e32 v134, 0x4800, v133
	global_store_dwordx4 v134, v[136:139], s[8:9] nt
	s_nop 1
	v_cvt_pk_bf16_f32 v136, v38, v39
	v_cvt_pk_bf16_f32 v137, v40, v41
	v_cvt_pk_bf16_f32 v138, v6, v7
	v_cvt_pk_bf16_f32 v139, v8, v9
	s_nop 0
	v_permlane32_swap_b32_e32 v136, v138
	v_permlane32_swap_b32_e32 v137, v139
	s_nop 0
	v_permlane16_swap_b32_e32 v136, v138
	v_permlane16_swap_b32_e32 v137, v139
	v_add_u32_e32 v134, 0x5000, v133
	global_store_dwordx4 v134, v[136:139], s[8:9] nt
	s_nop 1
	v_cvt_pk_bf16_f32 v136, v34, v35
	v_cvt_pk_bf16_f32 v137, v36, v37
	v_cvt_pk_bf16_f32 v138, v0, v1
	v_cvt_pk_bf16_f32 v139, v2, v3
	s_nop 0
	v_permlane32_swap_b32_e32 v136, v138
	v_permlane32_swap_b32_e32 v137, v139
	s_nop 0
	v_permlane16_swap_b32_e32 v136, v138
	v_permlane16_swap_b32_e32 v137, v139
	v_add_u32_e32 v134, 0x5800, v133
	global_store_dwordx4 v134, v[136:139], s[8:9] nt
	s_nop 1

; DI u16 f2bf(float x) { unsigned u = __float_as_uint(x); u += 0x7fffu + ((u >> 16) & 1u); return (u16)(u >> 16); }
; DI void phase_outproj(const Params& p, int layer, char* lds) {
;     ...
;     u16* yo = (u16*)(p.ws + OFF_XB) + base;
; #pragma unroll
;     for (int ai = 0; ai < 2; ++ai)
; #pragma unroll
;       for (int bj = 0; bj < 2; ++bj)
; #pragma unroll
;         for (int m = 0; m < 4; ++m) {
; #pragma unroll
;           for (int n = 0; n < 2; ++n)
; #pragma unroll
;             for (int j = 0; j < 4; ++j) yo[(ai * 128 + m * 16 + j) * DM + bj * 128 + n * 16] = f2bf(acc[ai][bj][m][n][j]);
;           __builtin_amdgcn_sched_barrier(0);
;         }
.LBB0_521:
	s_or_b64 exec, exec, s[8:9]
	s_nop 7
	v_and_b32_e32 v140, 64, v4
	v_and_b32_e32 v141, 15, v142
	v_add_u32_e32 v140, v140, v141
	v_bfe_u32 v141, v4, 2, 2
	v_and_b32_e32 v144, 0x60, v142
	v_lshl_add_u32 v144, v141, 3, v144
	v_lshlrev_b32_e32 v134, 11, v140
	v_lshl_add_u32 v134, v144, 1, v134
	s_lshl_b32 s10, s6, 11
	s_lshl_b32 s11, s4, 1
	s_add_u32 s10, s10, s11
	s_add_u32 s10, s78, s10
	s_addc_u32 s11, s79, 0
	v_cvt_pk_bf16_f32 v136, v126, v127
	v_cvt_pk_bf16_f32 v137, v128, v129
	v_cvt_pk_bf16_f32 v138, v122, v123
	v_cvt_pk_bf16_f32 v139, v124, v125
	s_nop 0
	v_permlane32_swap_b32_e32 v136, v138
	v_permlane32_swap_b32_e32 v137, v139
	s_nop 0
	v_permlane16_swap_b32_e32 v136, v138
	v_permlane16_swap_b32_e32 v137, v139
	global_store_dwordx4 v134, v[136:139], s[10:11] nt
	s_nop 1
	v_cvt_pk_bf16_f32 v136, v94, v95
	v_cvt_pk_bf16_f32 v137, v96, v97
	v_cvt_pk_bf16_f32 v138, v90, v91
	v_cvt_pk_bf16_f32 v139, v92, v93
	s_nop 0
	v_permlane32_swap_b32_e32 v136, v138
	v_permlane32_swap_b32_e32 v137, v139
	s_nop 0
	v_permlane16_swap_b32_e32 v136, v138
	v_permlane16_swap_b32_e32 v137, v139
	global_store_dwordx4 v134, v[136:139], s[10:11] offset:256 nt
	s_nop 1
	v_add_u32_e32 v135, 0x8000, v134
	v_cvt_pk_bf16_f32 v136, v118, v119
	v_cvt_pk_bf16_f32 v137, v120, v121
	v_cvt_pk_bf16_f32 v138, v114, v115
	v_cvt_pk_bf16_f32 v139, v116, v117
	s_nop 0
	v_permlane32_swap_b32_e32 v136, v138
	v_permlane32_swap_b32_e32 v137, v139
	s_nop 0
	v_permlane16_swap_b32_e32 v136, v138
	v_permlane16_swap_b32_e32 v137, v139
	global_store_dwordx4 v135, v[136:139], s[10:11] nt
	s_nop 1
	v_cvt_pk_bf16_f32 v136, v86, v87
	v_cvt_pk_bf16_f32 v137, v88, v89
	v_cvt_pk_bf16_f32 v138, v82, v83
	v_cvt_pk_bf16_f32 v139, v84, v85
	s_nop 0
	v_permlane32_swap_b32_e32 v136, v138
	v_permlane32_swap_b32_e32 v137, v139
	s_nop 0
	v_permlane16_swap_b32_e32 v136, v138
	v_permlane16_swap_b32_e32 v137, v139
	global_store_dwordx4 v135, v[136:139], s[10:11] offset:256 nt
	s_nop 1
	v_add_u32_e32 v135, 0x10000, v134
	v_cvt_pk_bf16_f32 v136, v110, v111
	v_cvt_pk_bf16_f32 v137, v112, v113
	v_cvt_pk_bf16_f32 v138, v106, v107
	v_cvt_pk_bf16_f32 v139, v108, v109
	s_nop 0
	v_permlane32_swap_b32_e32 v136, v138
	v_permlane32_swap_b32_e32 v137, v139
	s_nop 0
	v_permlane16_swap_b32_e32 v136, v138
	v_permlane16_swap_b32_e32 v137, v139
	global_store_dwordx4 v135, v[136:139], s[10:11] nt
	s_nop 1
	v_cvt_pk_bf16_f32 v136, v78, v79
	v_cvt_pk_bf16_f32 v137, v80, v81
	v_cvt_pk_bf16_f32 v138, v74, v75
	v_cvt_pk_bf16_f32 v139, v76, v77
	s_nop 0
	v_permlane32_swap_b32_e32 v136, v138
	v_permlane32_swap_b32_e32 v137, v139
	s_nop 0
	v_permlane16_swap_b32_e32 v136, v138
	v_permlane16_swap_b32_e32 v137, v139
	global_store_dwordx4 v135, v[136:139], s[10:11] offset:256 nt
	s_nop 1
	v_add_u32_e32 v135, 0x18000, v134
	v_cvt_pk_bf16_f32 v136, v102, v103
	v_cvt_pk_bf16_f32 v137, v104, v105
	v_cvt_pk_bf16_f32 v138, v98, v99
	v_cvt_pk_bf16_f32 v139, v100, v101
	s_nop 0
	v_permlane32_swap_b32_e32 v136, v138
	v_permlane32_swap_b32_e32 v137, v139
	s_nop 0
	v_permlane16_swap_b32_e32 v136, v138
	v_permlane16_swap_b32_e32 v137, v139
	global_store_dwordx4 v135, v[136:139], s[10:11] nt
	s_nop 1
	v_cvt_pk_bf16_f32 v136, v70, v71
	v_cvt_pk_bf16_f32 v137, v72, v73
	v_cvt_pk_bf16_f32 v138, v66, v67
	v_cvt_pk_bf16_f32 v139, v68, v69
	s_nop 0
	v_permlane32_swap_b32_e32 v136, v138
	v_permlane32_swap_b32_e32 v137, v139
	s_nop 0
	v_permlane16_swap_b32_e32 v136, v138
	v_permlane16_swap_b32_e32 v137, v139
	global_store_dwordx4 v135, v[136:139], s[10:11] offset:256 nt
	s_nop 1
	v_add_u32_e32 v135, 0x40000, v134
	v_cvt_pk_bf16_f32 v136, v62, v63
	v_cvt_pk_bf16_f32 v137, v64, v65
	v_cvt_pk_bf16_f32 v138, v58, v59
	v_cvt_pk_bf16_f32 v139, v60, v61
	s_nop 0
	v_permlane32_swap_b32_e32 v136, v138
	v_permlane32_swap_b32_e32 v137, v139
	s_nop 0
	v_permlane16_swap_b32_e32 v136, v138
	v_permlane16_swap_b32_e32 v137, v139
	global_store_dwordx4 v135, v[136:139], s[10:11] nt
	s_nop 1
	v_cvt_pk_bf16_f32 v136, v30, v31
	v_cvt_pk_bf16_f32 v137, v32, v33
	v_cvt_pk_bf16_f32 v138, v26, v27
	v_cvt_pk_bf16_f32 v139, v28, v29
	s_nop 0
	v_permlane32_swap_b32_e32 v136, v138
	v_permlane32_swap_b32_e32 v137, v139
	s_nop 0
	v_permlane16_swap_b32_e32 v136, v138
	v_permlane16_swap_b32_e32 v137, v139
	global_store_dwordx4 v135, v[136:139], s[10:11] offset:256 nt
	s_nop 1
	v_add_u32_e32 v135, 0x48000, v134
	v_cvt_pk_bf16_f32 v136, v54, v55
	v_cvt_pk_bf16_f32 v137, v56, v57
	v_cvt_pk_bf16_f32 v138, v50, v51
	v_cvt_pk_bf16_f32 v139, v52, v53
	s_nop 0
	v_permlane32_swap_b32_e32 v136, v138
	v_permlane32_swap_b32_e32 v137, v139
	s_nop 0
	v_permlane16_swap_b32_e32 v136, v138
	v_permlane16_swap_b32_e32 v137, v139
	global_store_dwordx4 v135, v[136:139], s[10:11] nt
	s_nop 1
	v_cvt_pk_bf16_f32 v136, v22, v23
	v_cvt_pk_bf16_f32 v137, v24, v25
	v_cvt_pk_bf16_f32 v138, v18, v19
	v_cvt_pk_bf16_f32 v139, v20, v21
	s_nop 0
	v_permlane32_swap_b32_e32 v136, v138
	v_permlane32_swap_b32_e32 v137, v139
	s_nop 0
	v_permlane16_swap_b32_e32 v136, v138
	v_permlane16_swap_b32_e32 v137, v139
	global_store_dwordx4 v135, v[136:139], s[10:11] offset:256 nt
	s_nop 1
	v_add_u32_e32 v135, 0x50000, v134
	v_cvt_pk_bf16_f32 v136, v46, v47
	v_cvt_pk_bf16_f32 v137, v48, v49
	v_cvt_pk_bf16_f32 v138, v42, v43
	v_cvt_pk_bf16_f32 v139, v44, v45
	s_nop 0
	v_permlane32_swap_b32_e32 v136, v138
	v_permlane32_swap_b32_e32 v137, v139
	s_nop 0
	v_permlane16_swap_b32_e32 v136, v138
	v_permlane16_swap_b32_e32 v137, v139
	global_store_dwordx4 v135, v[136:139], s[10:11] nt
	s_nop 1
	v_cvt_pk_bf16_f32 v136, v14, v15
	v_cvt_pk_bf16_f32 v137, v16, v17
	v_cvt_pk_bf16_f32 v138, v10, v11
	v_cvt_pk_bf16_f32 v139, v12, v13
	s_nop 0
	v_permlane32_swap_b32_e32 v136, v138
	v_permlane32_swap_b32_e32 v137, v139
	s_nop 0
	v_permlane16_swap_b32_e32 v136, v138
	v_permlane16_swap_b32_e32 v137, v139
	global_store_dwordx4 v135, v[136:139], s[10:11] offset:256 nt
	s_nop 1
	v_add_u32_e32 v135, 0x58000, v134
	v_cvt_pk_bf16_f32 v136, v38, v39
	v_cvt_pk_bf16_f32 v137, v40, v41
	v_cvt_pk_bf16_f32 v138, v34, v35
	v_cvt_pk_bf16_f32 v139, v36, v37
	s_nop 0
	v_permlane32_swap_b32_e32 v136, v138
	v_permlane32_swap_b32_e32 v137, v139
	s_nop 0
	v_permlane16_swap_b32_e32 v136, v138
	v_permlane16_swap_b32_e32 v137, v139
	global_store_dwordx4 v135, v[136:139], s[10:11] nt
	s_nop 1
	v_cvt_pk_bf16_f32 v136, v6, v7
	v_cvt_pk_bf16_f32 v137, v8, v9
	v_cvt_pk_bf16_f32 v138, v0, v1
	v_cvt_pk_bf16_f32 v139, v2, v3
	s_nop 0
	v_permlane32_swap_b32_e32 v136, v138
	v_permlane32_swap_b32_e32 v137, v139
	s_nop 0
	v_permlane16_swap_b32_e32 v136, v138
	v_permlane16_swap_b32_e32 v137, v139
	global_store_dwordx4 v135, v[136:139], s[10:11] offset:256 nt
	s_nop 1
	s_add_i32 s23, s23, s63
	v_readlane_b32 s4, v254, 54
	s_cmp_lt_i32 s23, s4
	s_cbranch_scc0 .LBB0_528

; DI unsigned pk2(float lo, float hi) { f32x2 v = {lo, hi}; b16x2 r = __builtin_convertvector(v, b16x2); return __builtin_bit_cast(unsigned, r); }
; DI float bflo(unsigned w) { return __uint_as_float(w << 16); }
; DI float bfhi(unsigned w) { return __uint_as_float(w & 0xffff0000u); }
; DI void phase_ln(const Params& p, int layer) {
;     ...
;   for (size_t row = (size_t)blockIdx.x * 8 + w; row < (size_t)T; row += (size_t)gridDim.x * 8) {
;     f32x4 v[4]; float sum = 0.f;
; #pragma unroll
;     for (int i = 0; i < 4; ++i) {
;       const f32x4 xv = *(const f32x4*)(xres + row * DM + 4 * lane + 256 * i);
;       const u32x2 yw = *(const u32x2*)(xb + row * DM + 4 * lane + 256 * i);
;       v[i][0] = ALPHA * xv[0] + bflo(yw[0]); v[i][1] = ALPHA * xv[1] + bfhi(yw[0]); v[i][2] = ALPHA * xv[2] + bflo(yw[1]); v[i][3] = ALPHA * xv[3] + bfhi(yw[1]);
;       sum += v[i][0] + v[i][1] + v[i][2] + v[i][3];
;     }
;     const float mu = wave_sum(sum) * (1.f / DM);
;     float sq = 0.f;
; #pragma unroll
;     for (int i = 0; i < 4; ++i)
; #pragma unroll
;       for (int j = 0; j < 4; ++j) { float d = v[i][j] - mu; sq += d * d; }
;     const float rstd = rsqrtf(wave_sum(sq) * (1.f / DM) + 1e-5f);
; #pragma unroll
;     for (int i = 0; i < 4; ++i) {
;       const int col = 4 * lane + 256 * i;
;       f32x4 g = *(const f32x4*)(lg + col), bb = *(const f32x4*)(lb + col), o;
; #pragma unroll
;       for (int j = 0; j < 4; ++j) o[j] = (v[i][j] - mu) * rstd * g[j] + bb[j];
;       *(f32x4*)(xout + row * DM + col) = o;
;       if (layer + 1 < DEPTH) {
;         u32x2 ow = {pk2(o[0], o[1]), pk2(o[2], o[3])};
;         *(u32x2*)(xb + row * DM + col) = ow;
;       }
.LBB0_543:
	v_lshl_add_u64 v[22:23], v[20:21], 0, v[4:5]
	global_load_dwordx4 v[30:33], v[22:23], off
	global_load_dwordx2 v[34:35], v[16:17], off offset:-1024
	global_load_dwordx4 v[0:3], v[22:23], off offset:1024
	global_load_dwordx2 v[42:43], v[16:17], off offset:-512
	global_load_dwordx4 v[6:9], v[22:23], off offset:2048
	global_load_dwordx2 v[28:29], v[16:17], off
	global_load_dwordx4 v[24:27], v[22:23], off offset:3072
	global_load_dwordx2 v[44:45], v[16:17], off offset:512
	s_mov_b32 s4, 0x3fd744fd
	s_waitcnt vmcnt(6)
	v_lshlrev_b32_e32 v48, 16, v35
	v_and_b32_e32 v49, 0xffff0000, v35
	v_pk_fma_f32 v[32:33], v[32:33], s[4:5], v[48:49] op_sel_hi:[1,0,1]
	v_lshlrev_b32_e32 v48, 16, v34
	v_and_b32_e32 v49, 0xffff0000, v34
	v_pk_fma_f32 v[30:31], v[30:31], s[4:5], v[48:49] op_sel_hi:[1,0,1]
	s_waitcnt vmcnt(0)
	v_lshlrev_b32_e32 v22, 16, v45
	v_and_b32_e32 v23, 0xffff0000, v45
	v_pk_fma_f32 v[22:23], v[26:27], s[4:5], v[22:23] op_sel_hi:[1,0,1]
	v_lshlrev_b32_e32 v26, 16, v44
	v_and_b32_e32 v27, 0xffff0000, v44
	v_pk_fma_f32 v[24:25], v[24:25], s[4:5], v[26:27] op_sel_hi:[1,0,1]
	v_lshlrev_b32_e32 v26, 16, v29
	v_and_b32_e32 v27, 0xffff0000, v29
	v_pk_fma_f32 v[26:27], v[8:9], s[4:5], v[26:27] op_sel_hi:[1,0,1]
	v_lshlrev_b32_e32 v8, 16, v28
	v_and_b32_e32 v9, 0xffff0000, v28
	v_pk_fma_f32 v[28:29], v[6:7], s[4:5], v[8:9] op_sel_hi:[1,0,1]
	v_mov_b32_e32 v7, v24
	v_mov_b32_e32 v6, v28
	v_mov_b32_e32 v8, v29
	v_mov_b32_e32 v9, v25
	v_pk_add_f32 v[6:7], v[6:7], v[8:9]
	v_mov_b32_e32 v8, v26
	v_mov_b32_e32 v9, v22
	v_pk_add_f32 v[6:7], v[8:9], v[6:7]
	v_mov_b32_e32 v8, v27
	v_mov_b32_e32 v9, v23
	v_pk_add_f32 v[44:45], v[8:9], v[6:7]
	v_lshlrev_b32_e32 v6, 16, v43
	v_and_b32_e32 v7, 0xffff0000, v43
	v_pk_fma_f32 v[46:47], v[2:3], s[4:5], v[6:7] op_sel_hi:[1,0,1]
	v_lshlrev_b32_e32 v2, 16, v42
	v_and_b32_e32 v3, 0xffff0000, v42
	v_pk_fma_f32 v[42:43], v[0:1], s[4:5], v[2:3] op_sel_hi:[1,0,1]
	v_mov_b32_e32 v34, v30
	v_mov_b32_e32 v35, v42
	v_mov_b32_e32 v48, v31
	v_mov_b32_e32 v49, v43
	v_pk_add_f32 v[34:35], v[34:35], v[48:49]
	v_mov_b32_e32 v48, v32
	v_mov_b32_e32 v49, v46
	v_pk_add_f32 v[34:35], v[48:49], v[34:35]
	v_mov_b32_e32 v48, v33
	v_mov_b32_e32 v49, v47
	v_pk_add_f32 v[34:35], v[48:49], v[34:35]
	global_load_dwordx4 v[0:3], v[12:13], off
	global_load_dwordx4 v[6:9], v[14:15], off
	v_add_f32_e32 v34, 0, v34
	v_add_f32_e32 v34, v34, v35
	v_add_f32_e32 v34, v34, v44
	v_add_f32_e32 v34, v34, v45
	ds_bpermute_b32 v35, v36, v34
	s_waitcnt lgkmcnt(0)
	v_add_f32_e32 v34, v34, v35
	ds_bpermute_b32 v35, v37, v34
	s_waitcnt lgkmcnt(0)
	v_add_f32_e32 v34, v34, v35
	ds_bpermute_b32 v35, v38, v34
	s_waitcnt lgkmcnt(0)
	v_add_f32_e32 v34, v34, v35
	ds_bpermute_b32 v35, v39, v34
	s_waitcnt lgkmcnt(0)
	v_add_f32_e32 v34, v34, v35
	ds_bpermute_b32 v35, v40, v34
	s_waitcnt lgkmcnt(0)
	v_add_f32_e32 v34, v34, v35
	ds_bpermute_b32 v35, v41, v34
	s_waitcnt lgkmcnt(0)
	v_add_f32_e32 v34, v34, v35
	v_mul_f32_e32 v34, 0x3a800000, v34
	v_pk_add_f32 v[44:45], v[30:31], v[34:35] op_sel_hi:[1,0] neg_lo:[0,1] neg_hi:[0,1]
	v_pk_add_f32 v[50:51], v[32:33], v[34:35] op_sel_hi:[1,0] neg_lo:[0,1] neg_hi:[0,1]
	v_pk_mul_f32 v[48:49], v[44:45], v[44:45]
	v_pk_mul_f32 v[52:53], v[50:51], v[50:51]
	v_add_f32_e32 v48, v48, v49
	v_pk_add_f32 v[30:31], v[42:43], v[34:35] op_sel_hi:[1,0] neg_lo:[0,1] neg_hi:[0,1]
	v_add_f32_e32 v48, v52, v48
	v_pk_mul_f32 v[42:43], v[30:31], v[30:31]
	v_add_f32_e32 v48, v53, v48
	v_pk_add_f32 v[32:33], v[46:47], v[34:35] op_sel_hi:[1,0] neg_lo:[0,1] neg_hi:[0,1]
	v_add_f32_e32 v42, v42, v48
	v_pk_mul_f32 v[46:47], v[32:33], v[32:33]
	v_add_f32_e32 v42, v43, v42
	v_pk_add_f32 v[28:29], v[28:29], v[34:35] op_sel_hi:[1,0] neg_lo:[0,1] neg_hi:[0,1]
	v_add_f32_e32 v42, v46, v42
	v_pk_mul_f32 v[54:55], v[28:29], v[28:29]
	v_add_f32_e32 v42, v47, v42
	v_pk_add_f32 v[26:27], v[26:27], v[34:35] op_sel_hi:[1,0] neg_lo:[0,1] neg_hi:[0,1]
	v_add_f32_e32 v42, v54, v42
	v_pk_mul_f32 v[56:57], v[26:27], v[26:27]
	v_add_f32_e32 v42, v55, v42
	v_pk_add_f32 v[24:25], v[24:25], v[34:35] op_sel_hi:[1,0] neg_lo:[0,1] neg_hi:[0,1]
	v_add_f32_e32 v42, v56, v42
	v_pk_mul_f32 v[58:59], v[24:25], v[24:25]
	v_add_f32_e32 v42, v57, v42
	v_pk_add_f32 v[22:23], v[22:23], v[34:35] op_sel_hi:[1,0] neg_lo:[0,1] neg_hi:[0,1]
	v_add_f32_e32 v42, v58, v42
	v_pk_mul_f32 v[34:35], v[22:23], v[22:23]
	v_add_f32_e32 v42, v59, v42
	v_add_f32_e32 v34, v34, v42
	v_add_f32_e32 v34, v35, v34
	ds_bpermute_b32 v35, v36, v34
	s_waitcnt lgkmcnt(0)
	v_add_f32_e32 v34, v34, v35
	ds_bpermute_b32 v35, v37, v34
	s_waitcnt lgkmcnt(0)
	v_add_f32_e32 v34, v34, v35
	ds_bpermute_b32 v35, v38, v34
	s_waitcnt lgkmcnt(0)
	v_add_f32_e32 v34, v34, v35
	ds_bpermute_b32 v35, v39, v34
	s_waitcnt lgkmcnt(0)
	v_add_f32_e32 v34, v34, v35
	ds_bpermute_b32 v35, v40, v34
	s_waitcnt lgkmcnt(0)
	v_add_f32_e32 v34, v34, v35
	ds_bpermute_b32 v35, v41, v34
	s_waitcnt lgkmcnt(0)
	v_add_f32_e32 v34, v34, v35
	v_mov_b32_e32 v35, 0x3727c5ac
	v_fmamk_f32 v34, v34, 0x3a800000, v35
	v_cmp_gt_f32_e32 vcc, s65, v34
	v_mul_f32_e32 v35, 0x4b800000, v34
	s_nop 0
	v_cndmask_b32_e32 v34, v34, v35, vcc
	v_rsq_f32_e32 v34, v34
	s_nop 0
	v_mul_f32_e32 v35, 0x45800000, v34
	v_cndmask_b32_e32 v34, v34, v35, vcc
	v_pk_mul_f32 v[42:43], v[44:45], v[34:35] op_sel_hi:[1,0]
	s_andn2_b64 vcc, exec, s[8:9]
	s_waitcnt vmcnt(0)
	v_pk_fma_f32 v[0:1], v[0:1], v[42:43], v[6:7]
	v_pk_mul_f32 v[6:7], v[50:51], v[34:35] op_sel_hi:[1,0]
	s_nop 0
	v_pk_fma_f32 v[2:3], v[2:3], v[6:7], v[8:9]
	v_cndmask_b32_e64 v8, 0, 1, s[8:9]
	v_lshl_add_u64 v[6:7], v[18:19], 0, v[4:5]
	v_cmp_ne_u32_e64 s[4:5], 1, v8
	global_store_dwordx4 v[6:7], v[0:3], off nt
	s_cbranch_vccnz .LBB0_545
	s_nop 0
	v_cvt_pk_bf16_f32 v0, v0, v1
	v_cvt_pk_bf16_f32 v1, v2, v3
	global_store_dwordx2 v[16:17], v[0:1], off offset:-1024 nt
; DI unsigned pk2(float lo, float hi) { f32x2 v = {lo, hi}; b16x2 r = __builtin_convertvector(v, b16x2); return __builtin_bit_cast(unsigned, r); }
; DI void phase_ln(const Params& p, int layer) {
;     ...
; #pragma unroll
;     for (int i = 0; i < 4; ++i) {
;       const int col = 4 * lane + 256 * i;
;       f32x4 g = *(const f32x4*)(lg + col), bb = *(const f32x4*)(lb + col), o;
; #pragma unroll
;       for (int j = 0; j < 4; ++j) o[j] = (v[i][j] - mu) * rstd * g[j] + bb[j];
;       *(f32x4*)(xout + row * DM + col) = o;
;       if (layer + 1 < DEPTH) {
;         u32x2 ow = {pk2(o[0], o[1]), pk2(o[2], o[3])};
;         *(u32x2*)(xb + row * DM + col) = ow;
;       }
;     }
.LBB0_545:
	global_load_dwordx4 v[0:3], v[12:13], off offset:1024
	s_nop 0
	global_load_dwordx4 v[42:45], v[14:15], off offset:1024
	v_mov_b32_e32 v35, v34
	v_pk_mul_f32 v[8:9], v[30:31], v[34:35]
	v_pk_mul_f32 v[30:31], v[32:33], v[34:35]
	s_and_b64 vcc, exec, s[4:5]
	s_waitcnt vmcnt(0)
	v_pk_fma_f32 v[0:1], v[8:9], v[0:1], v[42:43]
	v_pk_fma_f32 v[2:3], v[30:31], v[2:3], v[44:45]
	global_store_dwordx4 v[6:7], v[0:3], off offset:1024 nt
	s_cbranch_vccnz .LBB0_547
	s_nop 0
	v_cvt_pk_bf16_f32 v0, v0, v1
	v_cvt_pk_bf16_f32 v1, v2, v3
	global_store_dwordx2 v[16:17], v[0:1], off offset:-512 nt
.LBB0_547:
	global_load_dwordx4 v[0:3], v[12:13], off offset:2048
	s_nop 0
	global_load_dwordx4 v[30:33], v[14:15], off offset:2048
	v_pk_mul_f32 v[8:9], v[28:29], v[34:35]
	v_pk_mul_f32 v[26:27], v[26:27], v[34:35]
	s_and_b64 vcc, exec, s[4:5]
	s_waitcnt vmcnt(0)
	v_pk_fma_f32 v[0:1], v[8:9], v[0:1], v[30:31]
	v_pk_fma_f32 v[2:3], v[26:27], v[2:3], v[32:33]
	global_store_dwordx4 v[6:7], v[0:3], off offset:2048 nt
	s_cbranch_vccnz .LBB0_549
	s_nop 0
	v_cvt_pk_bf16_f32 v0, v0, v1
	v_cvt_pk_bf16_f32 v1, v2, v3
	global_store_dwordx2 v[16:17], v[0:1], off nt
.LBB0_549:
	global_load_dwordx4 v[0:3], v[12:13], off offset:3072
	s_nop 0
	global_load_dwordx4 v[26:29], v[14:15], off offset:3072
	v_pk_mul_f32 v[8:9], v[24:25], v[34:35]
	v_pk_mul_f32 v[22:23], v[22:23], v[34:35]
	s_and_b64 vcc, exec, s[4:5]
	s_waitcnt vmcnt(0)
	v_pk_fma_f32 v[0:1], v[8:9], v[0:1], v[26:27]
	v_pk_fma_f32 v[2:3], v[22:23], v[2:3], v[28:29]
	global_store_dwordx4 v[6:7], v[0:3], off offset:3072 nt
	s_cbranch_vccnz .LBB0_542
	s_nop 0
	v_cvt_pk_bf16_f32 v0, v0, v1
	v_cvt_pk_bf16_f32 v1, v2, v3
	global_store_dwordx2 v[16:17], v[0:1], off offset:512 nt
	s_branch .LBB0_542
